# combo6 + attention LDS-DMA hazard slots filled with useful ops + R3 decay log-gamma reused across items of the same head
# baseline (speedup 1.0000x reference)
.LBB0_169:
	s_andn2_b64 vcc, exec, s[6:7]
	s_cbranch_vccnz .LBB0_479
	v_readlane_b32 s3, v255, 14
	s_cmp_lt_i32 s3, 7
	s_mov_b64 s[6:7], -1
	s_cbranch_scc1 .LBB0_177
	v_readlane_b32 s3, v255, 14
	s_cmp_eq_u32 s3, 7
	s_cbranch_scc0 .LBB0_176
	s_cmpk_gt_i32 s92, 0x5ff
	s_cbranch_scc1 .LBB0_176
	s_load_dwordx4 s[8:11], s[0:1], 0x48
	s_load_dwordx2 s[6:7], s[0:1], 0x58
	s_waitcnt lgkmcnt(0)
	s_add_u32 s88, s78, 0x10800000
	s_addc_u32 s89, s79, 0
	s_add_u32 s72, s78, 0x13800000
	s_addc_u32 s73, s79, 0
	s_lshl_b32 s3, s93, 4
	s_add_u32 s82, s8, s3
	s_addc_u32 s83, s9, 0
	v_lshlrev_b32_e32 v0, 4, v192
	s_add_u32 s96, s10, s3
	v_and_b32_e32 v0, 0x70, v0
	v_add_u32_e32 v16, 0x200, v192
	s_addc_u32 s97, s11, 0
	v_writelane_b32 v255, s93, 19
	s_lshl_b32 s3, s93, 11
	v_lshl_add_u64 v[2:3], s[78:79], 0, v[0:1]
	s_mov_b64 s[8:9], 0xd800000
	v_ashrrev_i32_e32 v83, 3, v16
	v_ashrrev_i32_e32 v16, 4, v16
	s_add_u32 s6, s6, s3
	v_lshl_add_u64 v[30:31], v[2:3], 0, s[8:9]
	s_mov_b64 s[8:9], 0xf000000
	v_readlane_b32 s2, v255, 2
	v_readlane_b32 s3, v255, 3
	v_and_b32_e32 v38, -8, v16
	v_add_u32_e32 v16, 0x400, v192
	v_lshl_add_u64 v[32:33], v[2:3], 0, s[8:9]
	v_add_u32_e32 v3, 0, v0
	v_add_u32_e32 v9, s2, v0
	v_add_u32_e32 v10, s3, v0
	v_ashrrev_i32_e32 v0, 2, v192
	v_ashrrev_i32_e32 v16, 4, v16
	v_bfi_b32 v77, -16, v0, v192
	s_movk_i32 s8, 0x90
	v_and_b32_e32 v40, -8, v16
	v_add_u32_e32 v16, 0x600, v192
	v_bfe_u32 v4, v192, 4, 2
	v_mul_lo_u32 v0, v77, s8
	v_ashrrev_i32_e32 v82, 3, v192
	v_ashrrev_i32_e32 v16, 4, v16
	v_add_u32_e32 v11, 0, v0
	v_lshlrev_b32_e32 v0, 4, v4
	v_ashrrev_i32_e32 v17, 4, v192
	v_and_b32_e32 v42, -8, v16
	v_mul_lo_u32 v16, v82, s8
	v_and_b32_e32 v75, 0x7f, v192
	v_add_u32_e32 v14, s2, v0
	v_and_b32_e32 v36, -8, v17
	v_add_u32_e32 v84, v3, v16
	v_add_u32_e32 v85, v9, v16
	v_add_u32_e32 v86, v10, v16
	v_mul_lo_u32 v16, v83, s8
	s_movk_i32 s2, 0x110
	v_add_u32_e32 v87, v3, v16
	v_add_u32_e32 v88, v9, v16
	v_mul_lo_u32 v3, v36, s2
	v_lshlrev_b32_e32 v9, 1, v75
	v_add_u32_e32 v2, 1, v77
	v_add3_u32 v90, 0, v3, v9
	v_mul_lo_u32 v3, v38, s2
	v_cvt_f32_i32_e32 v78, v2
	v_sub_u32_e32 v2, 0x80, v77
	v_add3_u32 v91, 0, v3, v9
	v_mul_lo_u32 v3, v40, s2
	v_cvt_f32_i32_e32 v79, v2
	v_lshlrev_b32_e32 v2, 2, v4
	v_add3_u32 v92, 0, v3, v9
	v_mul_lo_u32 v3, v42, s2
	v_add3_u32 v93, 0, v3, v9
	v_sub_u32_e32 v9, v77, v2
	v_add_u32_e32 v89, v10, v16
	v_sub_u32_e32 v10, 0, v9
	v_cvt_f32_u32_e32 v94, v10
	v_xad_u32 v10, v2, -1, v77
	v_sub_u32_e32 v16, 0, v10
	v_cvt_f32_u32_e32 v96, v16
	v_or_b32_e32 v16, 2, v2
	v_sub_u32_e32 v16, v77, v16
	v_sub_u32_e32 v17, 0, v16
	v_cvt_f32_u32_e32 v98, v17
	v_or_b32_e32 v17, 3, v2
	v_sub_u32_e32 v17, v77, v17
	v_sub_u32_e32 v18, 0, v17
	v_cvt_f32_u32_e32 v100, v18
	v_or_b32_e32 v18, 16, v2
	v_sub_u32_e32 v18, v77, v18
	v_sub_u32_e32 v19, 0, v18
	v_cvt_f32_u32_e32 v102, v19
	v_or_b32_e32 v19, 17, v2
	v_sub_u32_e32 v19, v77, v19
	v_sub_u32_e32 v20, 0, v19
	v_cvt_f32_u32_e32 v104, v20
	v_or_b32_e32 v20, 18, v2
	v_sub_u32_e32 v20, v77, v20
	v_sub_u32_e32 v21, 0, v20
	v_cvt_f32_u32_e32 v106, v21
	v_or_b32_e32 v21, 19, v2
	v_sub_u32_e32 v21, v77, v21
	v_sub_u32_e32 v22, 0, v21
	v_cvt_f32_u32_e32 v108, v22
	v_or_b32_e32 v22, 32, v2
	v_sub_u32_e32 v22, v77, v22
	v_sub_u32_e32 v23, 0, v22
	v_cvt_f32_u32_e32 v110, v23
	v_or_b32_e32 v23, 33, v2
	v_sub_u32_e32 v23, v77, v23
	v_sub_u32_e32 v24, 0, v23
	v_cvt_f32_u32_e32 v112, v24
	v_or_b32_e32 v24, 34, v2
	v_sub_u32_e32 v24, v77, v24
	v_sub_u32_e32 v25, 0, v24
	v_cvt_f32_u32_e32 v114, v25
	v_or_b32_e32 v25, 35, v2
	v_sub_u32_e32 v25, v77, v25
	v_sub_u32_e32 v26, 0, v25
	v_cvt_f32_u32_e32 v116, v26
	v_or_b32_e32 v26, 48, v2
	v_sub_u32_e32 v26, v77, v26
	v_sub_u32_e32 v27, 0, v26
	v_cvt_f32_u32_e32 v118, v27
	v_or_b32_e32 v27, 49, v2
	v_sub_u32_e32 v27, v77, v27
	v_sub_u32_e32 v28, 0, v27
	v_cvt_f32_u32_e32 v120, v28
	v_or_b32_e32 v28, 50, v2
	v_sub_u32_e32 v28, v77, v28
	v_sub_u32_e32 v29, 0, v28
	v_cvt_f32_u32_e32 v122, v29
	v_or_b32_e32 v29, 51, v2
	v_sub_u32_e32 v29, v77, v29
	v_sub_u32_e32 v44, 0, v29
	v_cvt_f32_u32_e32 v124, v44
	v_or_b32_e32 v44, 64, v2
	v_sub_u32_e32 v44, v77, v44
	v_sub_u32_e32 v45, 0, v44
	v_cvt_f32_u32_e32 v126, v45
	v_or_b32_e32 v45, 0x41, v2
	v_sub_u32_e32 v45, v77, v45
	v_sub_u32_e32 v46, 0, v45
	v_cvt_f32_u32_e32 v128, v46
	v_or_b32_e32 v46, 0x42, v2
	v_sub_u32_e32 v46, v77, v46
	v_sub_u32_e32 v47, 0, v46
	v_cvt_f32_u32_e32 v130, v47
	v_or_b32_e32 v47, 0x43, v2
	v_sub_u32_e32 v47, v77, v47
	v_sub_u32_e32 v48, 0, v47
	v_cvt_f32_u32_e32 v132, v48
	v_or_b32_e32 v48, 0x50, v2
	v_sub_u32_e32 v48, v77, v48
	v_sub_u32_e32 v49, 0, v48
	v_cvt_f32_u32_e32 v134, v49
	v_or_b32_e32 v49, 0x51, v2
	v_sub_u32_e32 v49, v77, v49
	v_sub_u32_e32 v50, 0, v49
	v_cvt_f32_u32_e32 v136, v50
	v_or_b32_e32 v50, 0x52, v2
	v_sub_u32_e32 v50, v77, v50
	v_sub_u32_e32 v51, 0, v50
	v_cvt_f32_u32_e32 v138, v51
	v_or_b32_e32 v51, 0x53, v2
	v_sub_u32_e32 v51, v77, v51
	v_sub_u32_e32 v52, 0, v51
	v_cvt_f32_u32_e32 v140, v52
	v_or_b32_e32 v52, 0x60, v2
	v_sub_u32_e32 v52, v77, v52
	v_sub_u32_e32 v53, 0, v52
	v_cvt_f32_u32_e32 v142, v53
	v_or_b32_e32 v53, 0x61, v2
	v_sub_u32_e32 v53, v77, v53
	v_sub_u32_e32 v54, 0, v53
	v_cvt_f32_u32_e32 v144, v54
	v_or_b32_e32 v54, 0x62, v2
	v_sub_u32_e32 v54, v77, v54
	v_sub_u32_e32 v55, 0, v54
	v_cvt_f32_u32_e32 v146, v55
	v_or_b32_e32 v55, 0x63, v2
	v_sub_u32_e32 v55, v77, v55
	v_sub_u32_e32 v56, 0, v55
	v_cvt_f32_u32_e32 v148, v56
	v_or_b32_e32 v56, 0x70, v2
	v_sub_u32_e32 v56, v77, v56
	v_sub_u32_e32 v57, 0, v56
	v_cvt_f32_u32_e32 v150, v57
	v_or_b32_e32 v57, 0x71, v2
	v_sub_u32_e32 v57, v77, v57
	v_sub_u32_e32 v58, 0, v57
	v_add_u32_e32 v15, s3, v0
	v_cvt_f32_u32_e32 v152, v58
	v_or_b32_e32 v58, 0x72, v2
	v_cmp_gt_i32_e64 s[2:3], 0, v9
	v_sub_u32_e32 v58, v77, v58
	v_sub_u32_e32 v59, 0, v58
	v_writelane_b32 v255, s2, 20
	v_cvt_f32_u32_e32 v154, v59
	v_or_b32_e32 v59, 0x73, v2
	v_writelane_b32 v255, s3, 21
	v_cmp_gt_i32_e64 s[2:3], 0, v10
	v_sub_u32_e32 v59, v77, v59
	v_and_b32_e32 v8, 15, v192
	v_writelane_b32 v255, s2, 22
	v_sub_u32_e32 v60, 0, v59
	v_mul_u32_u24_e32 v3, 0x90, v8
	v_writelane_b32 v255, s3, 23
	v_cmp_gt_i32_e64 s[2:3], 0, v16
	v_cvt_f32_u32_e32 v156, v60
	v_mul_u32_u24_e32 v60, 0x110, v8
	v_writelane_b32 v255, s2, 24
	v_mul_u32_u24_e32 v8, 0x48, v8
	v_lshlrev_b32_e32 v13, 3, v4
	v_writelane_b32 v255, s3, 25
	v_cmp_gt_i32_e64 s[2:3], 0, v17
	v_lshlrev_b32_e32 v8, 1, v8
	v_add3_u32 v158, 0, v60, v13
	v_writelane_b32 v255, s2, 26
	v_add_u32_e32 v13, 0x900, v8
	v_cmp_lt_i32_e32 vcc, v239, v244
	v_writelane_b32 v255, s3, 27
	v_cmp_gt_i32_e64 s[2:3], 0, v18
	v_add_u32_e32 v162, v14, v13
	v_add_u32_e32 v163, v15, v13
	v_add_u32_e32 v13, 0x1200, v8
	v_writelane_b32 v255, s2, 28
	s_addc_u32 s7, s7, 0
	v_cndmask_b32_e32 v4, v234, v239, vcc
	v_cmp_lt_i32_e32 vcc, v240, v244
	v_lshlrev_b32_e32 v6, 6, v82
	v_add_u32_e32 v165, v14, v13
	v_add_u32_e32 v166, v15, v13
	v_add_u32_e32 v13, 0x1b00, v8
	v_writelane_b32 v255, s3, 29
	v_cmp_gt_i32_e64 s[2:3], 0, v19
	s_ashr_i32 s93, s92, 31
	v_lshlrev_b32_e32 v80, 2, v4
	v_cndmask_b32_e32 v4, v234, v240, vcc
	v_ashrrev_i32_e32 v7, 31, v6
	v_cvt_f32_u32_e32 v95, v9
	v_cvt_f32_u32_e32 v97, v10
	v_cvt_f32_u32_e32 v99, v16
	v_cvt_f32_u32_e32 v101, v17
	v_cvt_f32_u32_e32 v103, v18
	v_cvt_f32_u32_e32 v105, v19
	v_cvt_f32_u32_e32 v107, v20
	v_cvt_f32_u32_e32 v109, v21
	v_cvt_f32_u32_e32 v111, v22
	v_cvt_f32_u32_e32 v113, v23
	v_cvt_f32_u32_e32 v115, v24
	v_cvt_f32_u32_e32 v117, v25
	v_cvt_f32_u32_e32 v119, v26
	v_cvt_f32_u32_e32 v121, v27
	v_cvt_f32_u32_e32 v123, v28
	v_cvt_f32_u32_e32 v125, v29
	v_cvt_f32_u32_e32 v127, v44
	v_cvt_f32_u32_e32 v129, v45
	v_cvt_f32_u32_e32 v131, v46
	v_cvt_f32_u32_e32 v133, v47
	v_cvt_f32_u32_e32 v135, v48
	v_cvt_f32_u32_e32 v137, v49
	v_cvt_f32_u32_e32 v139, v50
	v_cvt_f32_u32_e32 v141, v51
	v_cvt_f32_u32_e32 v143, v52
	v_cvt_f32_u32_e32 v145, v53
	v_cvt_f32_u32_e32 v147, v54
	v_cvt_f32_u32_e32 v149, v55
	v_cvt_f32_u32_e32 v151, v56
	v_cvt_f32_u32_e32 v153, v57
	v_cvt_f32_u32_e32 v155, v58
	v_cvt_f32_u32_e32 v157, v59
	v_add_u32_e32 v168, v14, v13
	v_add_u32_e32 v169, v15, v13
	v_add_u32_e32 v13, 0x2400, v8
	v_writelane_b32 v255, s2, 30
	s_lshl_b64 s[14:15], s[92:93], 15
	v_lshlrev_b32_e32 v81, 2, v4
	v_lshlrev_b32_e32 v4, 6, v83
	v_add_u32_e32 v171, v14, v13
	v_add_u32_e32 v172, v15, v13
	v_add_u32_e32 v13, 0x2d00, v8
	v_writelane_b32 v255, s3, 31
	v_cmp_gt_i32_e64 s[2:3], 0, v20
	v_cmp_gt_i32_e64 s[40:41], 0, v44
	v_cmp_gt_i32_e64 s[42:43], 0, v45
	v_lshlrev_b64 v[44:45], 1, v[6:7]
	v_and_b32_e32 v6, 7, v192
	s_add_u32 s14, s78, s14
	v_add_u32_e32 v12, 0, v0
	v_ashrrev_i32_e32 v5, 31, v4
	v_add_u32_e32 v159, v14, v8
	v_add_u32_e32 v160, v15, v8
	v_add_u32_e32 v174, v14, v13
	v_add_u32_e32 v175, v15, v13
	v_add_u32_e32 v13, 0x3600, v8
	v_add_u32_e32 v8, 0x3f00, v8
	v_writelane_b32 v255, s2, 32
	v_lshlrev_b32_e32 v6, 4, v6
	v_mov_b32_e32 v7, v1
	s_addc_u32 s15, s79, s15
	s_ashr_i32 s81, s80, 31
	v_lshl_add_u64 v[34:35], s[6:7], 0, v[0:1]
	v_ashrrev_i32_e32 v37, 31, v36
	v_ashrrev_i32_e32 v39, 31, v38
	v_ashrrev_i32_e32 v41, 31, v40
	v_ashrrev_i32_e32 v43, 31, v42
	v_add_u32_e32 v161, 0x1100, v158
	v_add_u32_e32 v164, 0x2200, v158
	v_add_u32_e32 v167, 0x3300, v158
	v_add_u32_e32 v170, 0x4400, v158
	v_add_u32_e32 v173, 0x5500, v158
	v_add_u32_e32 v176, 0x6600, v158
	v_add_u32_e32 v177, v14, v13
	v_add_u32_e32 v178, v15, v13
	v_add_u32_e32 v179, 0x7700, v158
	v_add_u32_e32 v180, v14, v8
	v_add_u32_e32 v181, v15, v8
	v_writelane_b32 v255, s3, 33
	v_cmp_gt_i32_e64 s[20:21], 0, v21
	v_cmp_gt_i32_e64 s[22:23], 0, v22
	v_cmp_gt_i32_e64 s[24:25], 0, v23
	v_cmp_gt_i32_e64 s[26:27], 0, v24
	v_cmp_gt_i32_e64 s[28:29], 0, v25
	v_cmp_gt_i32_e64 s[30:31], 0, v26
	v_cmp_gt_i32_e64 s[34:35], 0, v27
	v_cmp_gt_i32_e64 s[36:37], 0, v28
	v_cmp_gt_i32_e64 s[38:39], 0, v29
	v_cmp_gt_i32_e64 s[44:45], 0, v46
	v_cmp_gt_i32_e64 s[46:47], 0, v47
	v_cmp_gt_i32_e64 s[48:49], 0, v48
	v_cmp_gt_i32_e64 s[50:51], 0, v49
	v_cmp_gt_i32_e64 s[52:53], 0, v50
	v_cmp_gt_i32_e64 s[54:55], 0, v51
	v_cmp_gt_i32_e64 s[6:7], 0, v52
	v_cmp_gt_i32_e64 s[8:9], 0, v53
	v_cmp_gt_i32_e64 s[10:11], 0, v54
	v_cmp_gt_i32_e64 s[12:13], 0, v55
	v_cmp_gt_i32_e64 s[64:65], 0, v56
	v_cmp_gt_i32_e64 s[66:67], 0, v57
	v_cmp_gt_i32_e64 s[68:69], 0, v58
	v_cmp_gt_i32_e64 s[70:71], 0, v59
	v_lshl_add_u64 v[46:47], s[14:15], 0, v[6:7]
	s_lshl_b64 s[76:77], s[80:81], 15
	v_lshlrev_b64 v[48:49], 1, v[4:5]
	s_lshl_b32 s3, s92, 5
	s_lshl_b32 s63, s80, 5
	v_add_u32_e32 v182, v11, v0
	v_add_u32_e32 v183, v12, v3
	v_lshlrev_b32_e32 v0, 1, v2
	s_mov_b32 s81, s92
	s_mov_b32 s19, 0x1c800000
	s_mov_b32 s32, -1
.LBB0_174:
	s_and_b32 s14, s81, 3
	s_lshl_b32 s74, s14, 2
	v_mov_b32_e32 v18, s74
	s_cmp_eq_u32 s14, s32
	s_cbranch_scc1 .Lr3_noload
	global_load_dword v2, v18, s[82:83]
	global_load_dword v193, v18, s[96:97]
.Lr3_noload:
	s_mov_b32 s84, 0x3fb8aa3b
	s_mov_b32 s2, 0xc2ce8ed0
	s_mov_b32 s93, 0x42b17218
	s_mov_b32 s16, 0x3f2aaaab
	s_mov_b32 s17, 0x3f317218
	s_mov_b32 s18, 0x33800000
	s_and_b32 s15, s3, 0xffffff80
	v_lshl_add_u64 v[20:21], v[46:47], 0, v[44:45]
	v_add_u32_e32 v24, s15, v83
	v_ashrrev_i32_e32 v25, 31, v24
	v_lshlrev_b64 v[28:29], 9, v[24:25]
	v_add_u32_e32 v188, 0x9000, v176
	s_add_i32 s81, s81, s80
	s_add_i32 s3, s3, s63
	s_cmp_eq_u32 s14, s32
	s_cbranch_scc1 .Lr3_reuse
	s_waitcnt vmcnt(1)
	v_mul_f32_e32 v3, 0x3fb8aa3b, v2
	v_fma_f32 v4, v2, s84, -v3
	v_rndne_f32_e32 v5, v3
	v_fmac_f32_e32 v4, 0x32a5705f, v2
	v_sub_f32_e32 v3, v3, v5
	v_add_f32_e32 v3, v3, v4
	v_exp_f32_e32 v3, v3
	v_cvt_i32_f32_e32 v4, v5
	v_cmp_ngt_f32_e32 vcc, s2, v2
	v_ldexp_f32 v3, v3, v4
	s_nop 0
	v_cndmask_b32_e32 v3, 0, v3, vcc
	v_cmp_nlt_f32_e32 vcc, s93, v2
	s_nop 1
	v_cndmask_b32_e32 v19, v245, v3, vcc
	v_sub_f32_e32 v4, 1.0, v19
	v_add_f32_e32 v2, -1.0, v4
	v_sub_f32_e32 v3, v2, v4
	v_add_f32_e32 v3, 1.0, v3
	v_sub_f32_e64 v2, -v19, v2
	v_add_f32_e32 v5, v2, v3
	v_frexp_mant_f32_e32 v2, v4
	v_cmp_gt_f32_e32 vcc, s16, v2
	v_cvt_f64_f32_e32 v[2:3], v4
	v_frexp_exp_i32_f64_e32 v2, v[2:3]
	v_subbrev_co_u32_e32 v10, vcc, 0, v2, vcc
	v_sub_u32_e32 v2, 0, v10
	v_ldexp_f32 v3, v4, v2
	v_add_f32_e32 v4, -1.0, v3
	v_add_f32_e32 v6, 1.0, v3
	v_ldexp_f32 v2, v5, v2
	v_add_f32_e32 v5, 1.0, v4
	v_add_f32_e32 v7, -1.0, v6
	v_sub_f32_e32 v5, v3, v5
	v_sub_f32_e32 v3, v3, v7
	v_add_f32_e32 v5, v2, v5
	v_add_f32_e32 v2, v2, v3
	v_add_f32_e32 v11, v6, v2
	v_rcp_f32_e32 v13, v11
	v_sub_f32_e32 v3, v11, v6
	v_sub_f32_e32 v12, v2, v3
	v_add_f32_e32 v3, v4, v5
	v_mul_f32_e32 v15, v3, v13
	v_sub_f32_e32 v2, v3, v4
	v_mul_f32_e32 v4, v11, v15
	v_fma_f32 v6, v15, v11, -v4
	v_fmac_f32_e32 v6, v15, v12
	v_sub_f32_e32 v14, v5, v2
	v_add_f32_e32 v2, v4, v6
	v_sub_f32_e32 v5, v3, v2
	v_pk_add_f32 v[8:9], v[2:3], v[4:5] neg_lo:[0,1] neg_hi:[0,1]
	v_mov_b32_e32 v7, v2
	v_pk_add_f32 v[2:3], v[8:9], v[6:7] neg_lo:[0,1] neg_hi:[0,1]
	v_cmp_nlt_f32_e32 vcc, 1.0, v19
	v_add_f32_e32 v3, v14, v3
	v_add_f32_e32 v2, v2, v3
	v_add_f32_e32 v3, v5, v2
	v_mul_f32_e32 v14, v13, v3
	v_mul_f32_e32 v4, v11, v14
	v_fma_f32 v6, v14, v11, -v4
	v_fmac_f32_e32 v6, v14, v12
	v_sub_f32_e32 v5, v5, v3
	v_add_f32_e32 v11, v2, v5
	v_add_f32_e32 v2, v4, v6
	v_sub_f32_e32 v5, v3, v2
	v_pk_add_f32 v[8:9], v[2:3], v[4:5] neg_lo:[0,1] neg_hi:[0,1]
	v_mov_b32_e32 v7, v2
	v_pk_add_f32 v[2:3], v[8:9], v[6:7] neg_lo:[0,1] neg_hi:[0,1]
	v_cmp_lt_f32_e64 s[74:75], |v19|, s18
	v_add_f32_e32 v3, v11, v3
	v_add_f32_e32 v2, v2, v3
	v_add_f32_e32 v3, v15, v14
	v_add_f32_e32 v2, v5, v2
	v_sub_f32_e32 v4, v3, v15
	v_mul_f32_e32 v2, v13, v2
	v_sub_f32_e32 v4, v14, v4
	v_add_f32_e32 v4, v4, v2
	v_add_f32_e32 v6, v3, v4
	v_mul_f32_e32 v7, v6, v6
	v_fmamk_f32 v2, v7, 0x3e9b6dac, v237
	v_fmaak_f32 v191, v7, v2, 0x3f2aaada
	v_cvt_f32_i32_e32 v2, v10
	v_sub_f32_e32 v3, v6, v3
	v_sub_f32_e32 v3, v4, v3
	v_ldexp_f32 v8, v3, 1
	v_mul_f32_e32 v3, v6, v7
	v_ldexp_f32 v5, v6, 1
	v_pk_mul_f32 v[6:7], v[2:3], v[190:191]
	s_nop 0
	v_fma_f32 v4, v2, s17, -v6
	v_fmac_f32_e32 v4, 0xb102e308, v2
	v_pk_add_f32 v[2:3], v[6:7], v[4:5]
	s_nop 0
	v_sub_f32_e32 v5, v3, v5
	v_sub_f32_e32 v5, v7, v5
	v_add_f32_e32 v9, v8, v5
	v_mov_b32_e32 v8, v6
	v_pk_add_f32 v[6:7], v[2:3], v[6:7] neg_lo:[0,1] neg_hi:[0,1]
	v_pk_add_f32 v[10:11], v[2:3], v[8:9]
	v_mov_b32_e32 v5, v2
	v_mov_b32_e32 v7, v11
	v_pk_add_f32 v[12:13], v[4:5], v[6:7] neg_lo:[0,1] neg_hi:[0,1]
	v_pk_add_f32 v[4:5], v[4:5], v[6:7]
	v_mov_b32_e32 v16, v3
	v_pk_add_f32 v[6:7], v[4:5], v[2:3] op_sel:[1,0] op_sel_hi:[0,1] neg_lo:[0,1] neg_hi:[0,1]
	v_pk_add_f32 v[14:15], v[10:11], v[6:7] op_sel_hi:[1,0] neg_lo:[0,1] neg_hi:[0,1]
	v_mov_b32_e32 v10, v11
	v_mov_b32_e32 v11, v5
	v_mov_b32_e32 v17, v6
	v_pk_add_f32 v[6:7], v[10:11], v[16:17] neg_lo:[0,1] neg_hi:[0,1]
	v_mov_b32_e32 v8, v9
	v_mov_b32_e32 v9, v2
	v_pk_add_f32 v[2:3], v[8:9], v[6:7] neg_lo:[0,1] neg_hi:[0,1]
	v_mov_b32_e32 v14, v12
	v_pk_add_f32 v[6:7], v[14:15], v[2:3]
	v_mov_b32_e32 v13, v5
	v_pk_add_f32 v[8:9], v[6:7], v[6:7] op_sel:[0,1] op_sel_hi:[1,0]
	s_nop 0
	v_pk_add_f32 v[4:5], v[4:5], v[8:9] op_sel:[1,0] op_sel_hi:[0,1]
	v_mov_b32_e32 v7, v4
	v_pk_add_f32 v[10:11], v[6:7], v[12:13] neg_lo:[0,1] neg_hi:[0,1]
	v_mov_b32_e32 v3, v8
	v_sub_f32_e32 v5, v6, v10
	v_pk_add_f32 v[2:3], v[2:3], v[10:11] neg_lo:[0,1] neg_hi:[0,1]
	v_sub_f32_e32 v5, v12, v5
	v_add_f32_e32 v2, v2, v5
	v_add_f32_e32 v2, v2, v3
	v_add_f32_e32 v2, v4, v2
	v_cndmask_b32_e32 v2, v241, v2, vcc
	v_cmp_neq_f32_e32 vcc, 1.0, v19
	s_nop 1
	v_cndmask_b32_e32 v2, v238, v2, vcc
	v_cndmask_b32_e64 v15, v2, -v19, s[74:75]
	s_waitcnt vmcnt(0)
	v_mov_b32_e32 v2, v193
	v_mul_f32_e32 v3, 0x3fb8aa3b, v2
	v_fma_f32 v4, v2, s84, -v3
	v_rndne_f32_e32 v5, v3
	v_fmac_f32_e32 v4, 0x32a5705f, v2
	v_sub_f32_e32 v3, v3, v5
	v_add_f32_e32 v3, v3, v4
	v_exp_f32_e32 v3, v3
	v_cvt_i32_f32_e32 v4, v5
	v_cmp_ngt_f32_e32 vcc, s2, v2
	s_lshl_b32 s84, s14, 7
	s_mov_b32 s2, 0x1c804000
	v_ldexp_f32 v3, v3, v4
	v_cndmask_b32_e32 v3, 0, v3, vcc
	v_cmp_nlt_f32_e32 vcc, s93, v2
	s_nop 1
	v_cndmask_b32_e32 v14, v245, v3, vcc
	v_sub_f32_e32 v4, 1.0, v14
	v_add_f32_e32 v2, -1.0, v4
	v_sub_f32_e32 v3, v2, v4
	v_add_f32_e32 v3, 1.0, v3
	v_sub_f32_e64 v2, -v14, v2
	v_add_f32_e32 v5, v2, v3
	v_frexp_mant_f32_e32 v2, v4
	v_cmp_gt_f32_e32 vcc, s16, v2
	v_cvt_f64_f32_e32 v[2:3], v4
	v_frexp_exp_i32_f64_e32 v2, v[2:3]
	v_subbrev_co_u32_e32 v10, vcc, 0, v2, vcc
	v_sub_u32_e32 v2, 0, v10
	v_ldexp_f32 v3, v4, v2
	v_add_f32_e32 v4, -1.0, v3
	v_add_f32_e32 v6, 1.0, v3
	v_ldexp_f32 v2, v5, v2
	v_add_f32_e32 v5, 1.0, v4
	v_add_f32_e32 v7, -1.0, v6
	v_sub_f32_e32 v5, v3, v5
	v_sub_f32_e32 v3, v3, v7
	v_add_f32_e32 v5, v2, v5
	v_add_f32_e32 v2, v2, v3
	v_add_f32_e32 v11, v6, v2
	v_rcp_f32_e32 v13, v11
	v_sub_f32_e32 v3, v11, v6
	v_sub_f32_e32 v12, v2, v3
	v_add_f32_e32 v3, v4, v5
	v_mul_f32_e32 v17, v3, v13
	v_sub_f32_e32 v2, v3, v4
	v_mul_f32_e32 v4, v11, v17
	v_fma_f32 v6, v17, v11, -v4
	v_fmac_f32_e32 v6, v17, v12
	v_sub_f32_e32 v16, v5, v2
	v_add_f32_e32 v2, v4, v6
	v_sub_f32_e32 v5, v3, v2
	v_pk_add_f32 v[8:9], v[2:3], v[4:5] neg_lo:[0,1] neg_hi:[0,1]
	v_mov_b32_e32 v7, v2
	v_pk_add_f32 v[2:3], v[8:9], v[6:7] neg_lo:[0,1] neg_hi:[0,1]
	v_cmp_nlt_f32_e32 vcc, 1.0, v14
	v_add_f32_e32 v3, v16, v3
	v_add_f32_e32 v2, v2, v3
	v_add_f32_e32 v3, v5, v2
	v_mul_f32_e32 v16, v13, v3
	v_mul_f32_e32 v4, v11, v16
	v_fma_f32 v6, v16, v11, -v4
	v_fmac_f32_e32 v6, v16, v12
	v_sub_f32_e32 v5, v5, v3
	v_add_f32_e32 v11, v2, v5
	v_add_f32_e32 v2, v4, v6
	v_sub_f32_e32 v5, v3, v2
	v_pk_add_f32 v[8:9], v[2:3], v[4:5] neg_lo:[0,1] neg_hi:[0,1]
	v_mov_b32_e32 v7, v2
	v_pk_add_f32 v[2:3], v[8:9], v[6:7] neg_lo:[0,1] neg_hi:[0,1]
	v_cmp_lt_f32_e64 s[74:75], |v14|, s18
	v_add_f32_e32 v3, v11, v3
	v_add_f32_e32 v2, v2, v3
	v_add_f32_e32 v3, v17, v16
	v_add_f32_e32 v2, v5, v2
	v_sub_f32_e32 v4, v3, v17
	v_mul_f32_e32 v2, v13, v2
	v_sub_f32_e32 v4, v16, v4
	v_add_f32_e32 v4, v4, v2
	v_add_f32_e32 v6, v3, v4
	v_mul_f32_e32 v7, v6, v6
	v_fmamk_f32 v2, v7, 0x3e9b6dac, v237
	v_fmaak_f32 v191, v7, v2, 0x3f2aaada
	v_cvt_f32_i32_e32 v2, v10
	v_sub_f32_e32 v3, v6, v3
	v_sub_f32_e32 v3, v4, v3
	v_ldexp_f32 v8, v3, 1
	v_mul_f32_e32 v3, v6, v7
	v_ldexp_f32 v5, v6, 1
	v_pk_mul_f32 v[6:7], v[2:3], v[190:191]
	s_nop 0
	v_fma_f32 v4, v2, s17, -v6
	v_fmac_f32_e32 v4, 0xb102e308, v2
	v_pk_add_f32 v[2:3], v[6:7], v[4:5]
	v_readlane_b32 s16, v255, 30
	v_sub_f32_e32 v5, v3, v5
	v_sub_f32_e32 v5, v7, v5
	v_add_f32_e32 v9, v8, v5
	v_mov_b32_e32 v8, v6
	v_pk_add_f32 v[6:7], v[2:3], v[6:7] neg_lo:[0,1] neg_hi:[0,1]
	v_pk_add_f32 v[10:11], v[2:3], v[8:9]
	v_mov_b32_e32 v5, v2
	v_mov_b32_e32 v7, v11
	v_pk_add_f32 v[12:13], v[4:5], v[6:7] neg_lo:[0,1] neg_hi:[0,1]
	v_pk_add_f32 v[4:5], v[4:5], v[6:7]
	v_mov_b32_e32 v18, v3
	v_pk_add_f32 v[6:7], v[4:5], v[2:3] op_sel:[1,0] op_sel_hi:[0,1] neg_lo:[0,1] neg_hi:[0,1]
	v_pk_add_f32 v[16:17], v[10:11], v[6:7] op_sel_hi:[1,0] neg_lo:[0,1] neg_hi:[0,1]
	v_mov_b32_e32 v10, v11
	v_mov_b32_e32 v11, v5
	v_mov_b32_e32 v19, v6
	v_pk_add_f32 v[6:7], v[10:11], v[18:19] neg_lo:[0,1] neg_hi:[0,1]
	v_mov_b32_e32 v8, v9
	v_mov_b32_e32 v9, v2
	v_pk_add_f32 v[2:3], v[8:9], v[6:7] neg_lo:[0,1] neg_hi:[0,1]
	v_mov_b32_e32 v16, v12
	v_pk_add_f32 v[6:7], v[16:17], v[2:3]
	v_mov_b32_e32 v13, v5
	v_pk_add_f32 v[8:9], v[6:7], v[6:7] op_sel:[0,1] op_sel_hi:[1,0]
	v_readlane_b32 s17, v255, 31
	v_pk_add_f32 v[4:5], v[4:5], v[8:9] op_sel:[1,0] op_sel_hi:[0,1]
	v_mov_b32_e32 v7, v4
	v_pk_add_f32 v[10:11], v[6:7], v[12:13] neg_lo:[0,1] neg_hi:[0,1]
	v_mov_b32_e32 v3, v8
	v_sub_f32_e32 v5, v6, v10
	v_pk_add_f32 v[2:3], v[2:3], v[10:11] neg_lo:[0,1] neg_hi:[0,1]
	v_sub_f32_e32 v5, v12, v5
	v_add_f32_e32 v2, v2, v5
	v_add_f32_e32 v2, v2, v3
	v_add_f32_e32 v2, v4, v2
	v_cndmask_b32_e32 v2, v241, v2, vcc
	v_cmp_neq_f32_e32 vcc, 1.0, v14
	v_lshl_add_u64 v[12:13], v[30:31], 0, s[84:85]
	v_lshl_add_u64 v[10:11], v[32:33], 0, s[84:85]
	v_cndmask_b32_e32 v2, v238, v2, vcc
	v_cndmask_b32_e64 v14, v2, -v14, s[74:75]
	v_mov_b32_e32 v189, v15
	v_mov_b32_e32 v193, v14
	s_mov_b32 s32, s14
	s_branch .Lr3_join
.Lr3_reuse:
	s_lshl_b32 s84, s14, 7
	s_mov_b32 s2, 0x1c804000
	v_readlane_b32 s16, v255, 30
	v_readlane_b32 s17, v255, 31
	v_lshl_add_u64 v[12:13], v[30:31], 0, s[84:85]
	v_lshl_add_u64 v[10:11], v[32:33], 0, s[84:85]
	v_mov_b32_e32 v15, v189
	v_mov_b32_e32 v14, v193
.Lr3_join:
	v_add_u32_e32 v2, s15, v82
	v_ashrrev_i32_e32 v3, 31, v2
	v_lshlrev_b64 v[6:7], 9, v[2:3]
	v_lshl_add_u64 v[2:3], v[12:13], 0, v[6:7]
	global_load_dwordx4 v[2:5], v[2:3], off
	v_lshl_add_u64 v[6:7], v[10:11], 0, v[6:7]
	global_load_dwordx4 v[6:9], v[6:7], off
	v_add_co_u32_e32 v16, vcc, s19, v20
	v_lshl_add_u64 v[12:13], v[12:13], 0, v[28:29]
	s_nop 0
	v_addc_co_u32_e32 v17, vcc, 0, v21, vcc
	v_add_co_u32_e32 v20, vcc, s2, v20
	v_lshl_add_u64 v[10:11], v[10:11], 0, v[28:29]
	s_nop 0
	v_addc_co_u32_e32 v21, vcc, 0, v21, vcc
	v_lshl_add_u64 v[28:29], v[46:47], 0, v[48:49]
	v_add_co_u32_e32 v50, vcc, s19, v28
	s_lshl_b32 s84, s14, 8
	s_nop 0
	v_addc_co_u32_e32 v51, vcc, 0, v29, vcc
	v_add_co_u32_e32 v28, vcc, s2, v28
	global_load_dwordx4 v[52:55], v[50:51], off
	s_nop 0
	v_addc_co_u32_e32 v29, vcc, 0, v29, vcc
	global_load_dwordx4 v[56:59], v[28:29], off
	v_or_b32_e32 v28, s15, v75
	v_ashrrev_i32_e32 v29, 31, v28
	v_lshlrev_b64 v[28:29], 10, v[28:29]
	v_lshl_add_u64 v[28:29], s[88:89], 0, v[28:29]
	v_lshl_add_u64 v[28:29], v[28:29], 0, s[84:85]
	global_load_dwordx4 v[16:19], v[16:17], off
	v_lshl_add_u64 v[60:61], v[36:37], 1, v[28:29]
	global_load_dwordx4 v[20:23], v[20:21], off
	v_lshl_add_u64 v[62:63], v[38:39], 1, v[28:29]
	global_load_dwordx4 v[24:27], v[12:13], off
	v_lshl_add_u64 v[64:65], v[40:41], 1, v[28:29]
	global_load_dwordx4 v[10:13], v[10:11], off
	s_waitcnt vmcnt(7)
	ds_write_b128 v84, v[2:5]
	s_waitcnt vmcnt(6)
	ds_write_b128 v84, v[6:9] offset:18432
	v_lshl_add_u64 v[28:29], v[42:43], 1, v[28:29]
	global_load_dwordx4 v[2:5], v[60:61], off
	global_load_dwordx4 v[6:9], v[62:63], off
	s_nop 0
	global_load_dwordx4 v[60:63], v[64:65], off
	s_nop 0
	global_load_dwordx4 v[64:67], v[28:29], off
	s_waitcnt vmcnt(7)
	ds_write_b128 v85, v[16:19]
	s_waitcnt vmcnt(6)
	ds_write_b128 v86, v[20:23]
	s_waitcnt vmcnt(5)
	ds_write_b128 v87, v[24:27]
	s_waitcnt vmcnt(4)
	ds_write_b128 v87, v[10:13] offset:18432
	ds_write_b128 v88, v[52:55]
	ds_write_b128 v89, v[56:59]
	s_waitcnt vmcnt(3)
	ds_write_b16 v90, v2 offset:36864
	ds_write_b16_d16_hi v90, v2 offset:37136
	ds_write_b16 v90, v3 offset:37408
	ds_write_b16_d16_hi v90, v3 offset:37680
	ds_write_b16 v90, v4 offset:37952
	ds_write_b16_d16_hi v90, v4 offset:38224
	ds_write_b16 v90, v5 offset:38496
	ds_write_b16_d16_hi v90, v5 offset:38768
	s_waitcnt vmcnt(2)
	ds_write_b16 v91, v6 offset:36864
	ds_write_b16_d16_hi v91, v6 offset:37136
	ds_write_b16 v91, v7 offset:37408
	ds_write_b16_d16_hi v91, v7 offset:37680
	ds_write_b16 v91, v8 offset:37952
	ds_write_b16_d16_hi v91, v8 offset:38224
	ds_write_b16 v91, v9 offset:38496
	ds_write_b16_d16_hi v91, v9 offset:38768
	s_waitcnt vmcnt(1)
	ds_write_b16 v92, v60 offset:36864
	ds_write_b16_d16_hi v92, v60 offset:37136
	ds_write_b16 v92, v61 offset:37408
	ds_write_b16_d16_hi v92, v61 offset:37680
	ds_write_b16 v92, v62 offset:37952
	ds_write_b16_d16_hi v92, v62 offset:38224
	ds_write_b16 v92, v63 offset:38496
	ds_write_b16_d16_hi v92, v63 offset:38768
	s_waitcnt vmcnt(0)
	ds_write_b16 v93, v64 offset:36864
	ds_write_b16_d16_hi v93, v64 offset:37136
	ds_write_b16 v93, v65 offset:37408
	ds_write_b16_d16_hi v93, v65 offset:37680
	ds_write_b16 v93, v66 offset:37952
	ds_write_b16_d16_hi v93, v66 offset:38224
	ds_write_b16 v93, v67 offset:38496
	ds_write_b16_d16_hi v93, v67 offset:38768
	v_add_u32_e32 v242, s15, v77
	v_ashrrev_i32_e32 v243, 31, v242
	v_lshlrev_b64 v[242:243], 10, v[242:243]
	v_lshl_add_u64 v[242:243], s[72:73], 0, v[242:243]
	v_lshl_add_u64 v[242:243], v[242:243], 0, s[84:85]
	v_lshl_add_u64 v[242:243], v[242:243], 0, v[0:1]
	global_load_dwordx2 v[206:207], v[242:243], off
	global_load_dwordx2 v[208:209], v[242:243], off offset:32
	global_load_dwordx2 v[210:211], v[242:243], off offset:64
	global_load_dwordx2 v[212:213], v[242:243], off offset:96
	global_load_dwordx2 v[214:215], v[242:243], off offset:128
	global_load_dwordx2 v[216:217], v[242:243], off offset:160
	global_load_dwordx2 v[218:219], v[242:243], off offset:192
	global_load_dwordx2 v[220:221], v[242:243], off offset:224
	s_waitcnt lgkmcnt(0)
	s_barrier
	ds_read_b128 v[6:9], v182
	ds_read_b128 v[2:5], v182 offset:64
	ds_read_b128 v[10:13], v183 offset:18432
	v_mul_f32_e32 v50, 0x3fb8aa3b, v15
	v_mul_f32_e32 v51, 0x3fb8aa3b, v14
	ds_read_b128 v[14:17], v183 offset:18496
	s_waitcnt lgkmcnt(1)
	v_mfma_f32_16x16x32_bf16 v[10:13], v[10:13], v[6:9], 0
	v_readlane_b32 s74, v255, 20
	v_readlane_b32 s75, v255, 21
	ds_read_b128 v[18:21], v183 offset:20800
	s_waitcnt lgkmcnt(1)
	v_mfma_f32_16x16x32_bf16 v[10:13], v[14:17], v[2:5], v[10:13]
	v_mul_f32_e32 v14, v51, v94
	v_mul_f32_e32 v15, v50, v95
	v_cndmask_b32_e64 v14, v15, v14, s[74:75]
	v_readlane_b32 s74, v255, 22
	v_mul_f32_e32 v15, v50, v97
	v_mul_f32_e32 v16, v51, v96
	v_readlane_b32 s75, v255, 23
	v_exp_f32_e32 v14, v14
	ds_read_b128 v[22:25], v183 offset:23104
	v_cndmask_b32_e64 v15, v15, v16, s[74:75]
	v_exp_f32_e32 v15, v15
	v_readlane_b32 s74, v255, 24
	v_readlane_b32 s75, v255, 25
	v_mul_f32_e32 v16, v51, v100
	v_pk_mul_f32 v[10:11], v[10:11], v[14:15]
	v_mul_f32_e32 v14, v50, v99
	v_mul_f32_e32 v15, v51, v98
	v_cndmask_b32_e64 v14, v14, v15, s[74:75]
	v_readlane_b32 s74, v255, 26
	v_mul_f32_e32 v15, v50, v101
	v_readlane_b32 s75, v255, 27
	v_exp_f32_e32 v14, v14
	ds_read_b128 v[26:29], v183 offset:25408
	v_cndmask_b32_e64 v15, v15, v16, s[74:75]
	v_exp_f32_e32 v15, v15
	v_readlane_b32 s74, v255, 28
	v_readlane_b32 s75, v255, 29
	ds_read_b128 v[52:55], v183 offset:27712
	v_pk_mul_f32 v[12:13], v[12:13], v[14:15]
	ds_read_b128 v[14:17], v183 offset:20736
	s_waitcnt lgkmcnt(0)
	v_mfma_f32_16x16x32_bf16 v[14:17], v[14:17], v[6:9], 0
	ds_read_b128 v[56:59], v183 offset:30016
	v_cvt_pk_bf16_f32 v10, v10, v11
	v_cvt_pk_bf16_f32 v11, v12, v13
	v_mfma_f32_16x16x32_bf16 v[14:17], v[18:21], v[2:5], v[14:17]
	v_mul_f32_e32 v18, v50, v103
	v_mul_f32_e32 v19, v51, v102
	v_cndmask_b32_e64 v18, v18, v19, s[74:75]
	v_mul_f32_e32 v19, v50, v105
	v_mul_f32_e32 v20, v51, v104
	v_cndmask_b32_e64 v19, v19, v20, s[16:17]
	v_exp_f32_e32 v18, v18
	v_exp_f32_e32 v19, v19
	v_readlane_b32 s16, v255, 32
	v_readlane_b32 s17, v255, 33
	v_mul_f32_e32 v20, v51, v108
	v_pk_mul_f32 v[14:15], v[18:19], v[14:15]
	v_mul_f32_e32 v18, v50, v107
	v_mul_f32_e32 v19, v51, v106
	v_cndmask_b32_e64 v18, v18, v19, s[16:17]
	v_mul_f32_e32 v19, v50, v109
	v_cndmask_b32_e64 v19, v19, v20, s[20:21]
	v_exp_f32_e32 v18, v18
	v_exp_f32_e32 v19, v19
	v_cvt_pk_bf16_f32 v12, v14, v15
	s_mov_b32 s74, 0xf800000
	v_lshl_add_u64 v[46:47], v[46:47], 0, s[76:77]
	v_pk_mul_f32 v[16:17], v[18:19], v[16:17]
	ds_read_b128 v[18:21], v183 offset:23040
	s_waitcnt lgkmcnt(0)
	v_mfma_f32_16x16x32_bf16 v[18:21], v[18:21], v[6:9], 0
	v_cvt_pk_bf16_f32 v13, v16, v17
	v_mfma_f32_16x16x32_bf16 v[18:21], v[22:25], v[2:5], v[18:21]
	v_mul_f32_e32 v22, v50, v111
	v_mul_f32_e32 v23, v51, v110
	v_cndmask_b32_e64 v22, v22, v23, s[22:23]
	v_mul_f32_e32 v23, v50, v113
	v_mul_f32_e32 v24, v51, v112
	v_cndmask_b32_e64 v23, v23, v24, s[24:25]
	v_exp_f32_e32 v22, v22
	v_exp_f32_e32 v23, v23
	v_mul_f32_e32 v24, v51, v116
	v_pk_mul_f32 v[18:19], v[22:23], v[18:19]
	v_mul_f32_e32 v22, v50, v115
	v_mul_f32_e32 v23, v51, v114
	v_cndmask_b32_e64 v22, v22, v23, s[26:27]
	v_mul_f32_e32 v23, v50, v117
	v_cndmask_b32_e64 v23, v23, v24, s[28:29]
	v_exp_f32_e32 v22, v22
	v_exp_f32_e32 v23, v23
	v_cvt_pk_bf16_f32 v14, v18, v19
	v_pk_mul_f32 v[20:21], v[22:23], v[20:21]
	ds_read_b128 v[22:25], v183 offset:25344
	s_waitcnt lgkmcnt(0)
	v_mfma_f32_16x16x32_bf16 v[22:25], v[22:25], v[6:9], 0
	v_cvt_pk_bf16_f32 v15, v20, v21
	v_mfma_f32_16x16x32_bf16 v[22:25], v[26:29], v[2:5], v[22:25]
	v_mul_f32_e32 v26, v50, v119
	v_mul_f32_e32 v27, v51, v118
	v_cndmask_b32_e64 v26, v26, v27, s[30:31]
	v_mul_f32_e32 v27, v50, v121
	v_mul_f32_e32 v28, v51, v120
	v_cndmask_b32_e64 v27, v27, v28, s[34:35]
	v_exp_f32_e32 v26, v26
	v_exp_f32_e32 v27, v27
	v_mul_f32_e32 v28, v51, v124
	v_pk_mul_f32 v[22:23], v[26:27], v[22:23]
	v_mul_f32_e32 v26, v50, v123
	v_mul_f32_e32 v27, v51, v122
	v_cndmask_b32_e64 v26, v26, v27, s[36:37]
	v_mul_f32_e32 v27, v50, v125
	v_cndmask_b32_e64 v27, v27, v28, s[38:39]
	v_exp_f32_e32 v26, v26
	v_exp_f32_e32 v27, v27
	v_cvt_pk_bf16_f32 v16, v22, v23
	v_pk_mul_f32 v[24:25], v[26:27], v[24:25]
	ds_read_b128 v[26:29], v183 offset:27648
	s_waitcnt lgkmcnt(0)
	v_mfma_f32_16x16x32_bf16 v[26:29], v[26:29], v[6:9], 0
	v_cvt_pk_bf16_f32 v17, v24, v25
	v_mfma_f32_16x16x32_bf16 v[26:29], v[52:55], v[2:5], v[26:29]
	v_mul_f32_e32 v52, v50, v127
	v_mul_f32_e32 v53, v51, v126
	v_cndmask_b32_e64 v52, v52, v53, s[40:41]
	v_mul_f32_e32 v53, v50, v129
	v_mul_f32_e32 v54, v51, v128
	v_cndmask_b32_e64 v53, v53, v54, s[42:43]
	v_exp_f32_e32 v52, v52
	v_exp_f32_e32 v53, v53
	v_mul_f32_e32 v54, v51, v132
	v_pk_mul_f32 v[26:27], v[52:53], v[26:27]
	v_mul_f32_e32 v52, v50, v131
	v_mul_f32_e32 v53, v51, v130
	v_cndmask_b32_e64 v52, v52, v53, s[44:45]
	v_mul_f32_e32 v53, v50, v133
	v_cndmask_b32_e64 v53, v53, v54, s[46:47]
	v_exp_f32_e32 v52, v52
	v_exp_f32_e32 v53, v53
	v_cvt_pk_bf16_f32 v18, v26, v27
	v_mul_f32_e32 v26, v50, v78
	v_exp_f32_e32 v74, v26
	v_pk_mul_f32 v[28:29], v[52:53], v[28:29]
	ds_read_b128 v[52:55], v183 offset:29952
	s_waitcnt lgkmcnt(0)
	v_mfma_f32_16x16x32_bf16 v[52:55], v[52:55], v[6:9], 0
	v_mul_f32_e32 v26, v51, v79
	v_cvt_pk_bf16_f32 v19, v28, v29
	v_exp_f32_e32 v76, v26
	v_mfma_f32_16x16x32_bf16 v[52:55], v[56:59], v[2:5], v[52:55]
	v_mul_f32_e32 v56, v50, v135
	v_mul_f32_e32 v57, v51, v134
	v_cndmask_b32_e64 v56, v56, v57, s[48:49]
	v_mul_f32_e32 v57, v50, v137
	v_mul_f32_e32 v58, v51, v136
	v_cndmask_b32_e64 v57, v57, v58, s[50:51]
	v_exp_f32_e32 v56, v56
	v_exp_f32_e32 v57, v57
	s_nop 0
	v_pk_mul_f32 v[60:61], v[56:57], v[52:53]
	v_mul_f32_e32 v52, v50, v139
	v_mul_f32_e32 v53, v51, v138
	v_cndmask_b32_e64 v52, v52, v53, s[52:53]
	v_mul_f32_e32 v53, v50, v141
	v_mul_f32_e32 v56, v51, v140
	v_cndmask_b32_e64 v53, v53, v56, s[54:55]
	v_exp_f32_e32 v52, v52
	v_exp_f32_e32 v53, v53
	ds_read_b128 v[56:59], v183 offset:32320
	v_cvt_pk_bf16_f32 v20, v60, v61
	v_pk_mul_f32 v[62:63], v[52:53], v[54:55]
	ds_read_b128 v[52:55], v183 offset:32256
	s_waitcnt lgkmcnt(0)
	v_mfma_f32_16x16x32_bf16 v[52:55], v[52:55], v[6:9], 0
	v_cvt_pk_bf16_f32 v21, v62, v63
	v_mfma_f32_16x16x32_bf16 v[52:55], v[56:59], v[2:5], v[52:55]
	v_mul_f32_e32 v56, v50, v143
	v_mul_f32_e32 v57, v51, v142
	v_cndmask_b32_e64 v56, v56, v57, s[6:7]
	v_mul_f32_e32 v57, v50, v145
	v_mul_f32_e32 v58, v51, v144
	v_cndmask_b32_e64 v57, v57, v58, s[8:9]
	v_exp_f32_e32 v56, v56
	v_exp_f32_e32 v57, v57
	s_nop 0
	v_pk_mul_f32 v[64:65], v[56:57], v[52:53]
	v_mul_f32_e32 v52, v50, v147
	v_mul_f32_e32 v53, v51, v146
	v_cndmask_b32_e64 v52, v52, v53, s[10:11]
	v_mul_f32_e32 v53, v50, v149
	v_mul_f32_e32 v56, v51, v148
	v_cndmask_b32_e64 v53, v53, v56, s[12:13]
	v_exp_f32_e32 v52, v52
	v_exp_f32_e32 v53, v53
	ds_read_b128 v[56:59], v183 offset:34624
	v_cvt_pk_bf16_f32 v22, v64, v65
	v_pk_mul_f32 v[66:67], v[52:53], v[54:55]
	ds_read_b128 v[52:55], v183 offset:34560
	s_waitcnt lgkmcnt(0)
	v_mfma_f32_16x16x32_bf16 v[52:55], v[52:55], v[6:9], 0
	v_cvt_pk_bf16_f32 v23, v66, v67
	v_mfma_f32_16x16x32_bf16 v[52:55], v[56:59], v[2:5], v[52:55]
	v_mul_f32_e32 v56, v50, v151
	v_mul_f32_e32 v57, v51, v150
	v_cndmask_b32_e64 v56, v56, v57, s[64:65]
	v_mul_f32_e32 v57, v50, v153
	v_mul_f32_e32 v58, v51, v152
	v_cndmask_b32_e64 v57, v57, v58, s[66:67]
	v_exp_f32_e32 v56, v56
	v_exp_f32_e32 v57, v57
	v_mul_f32_e32 v58, v51, v156
	v_pk_mul_f32 v[52:53], v[56:57], v[52:53]
	v_mul_f32_e32 v56, v50, v155
	v_mul_f32_e32 v57, v51, v154
	v_cndmask_b32_e64 v56, v56, v57, s[68:69]
	v_mul_f32_e32 v57, v50, v157
	v_cndmask_b32_e64 v57, v57, v58, s[70:71]
	v_exp_f32_e32 v56, v56
	v_exp_f32_e32 v57, v57
	v_cvt_pk_bf16_f32 v24, v52, v53
	v_pk_mul_f32 v[54:55], v[56:57], v[54:55]
	s_nop 0
	v_cvt_pk_bf16_f32 v25, v54, v55
	v_add_u32_e32 v54, 0x9000, v158
	ds_read2_b64 v[26:29], v54 offset1:4
	ds_read2_b64 v[50:53], v54 offset0:8 offset1:12
	ds_read2_b64 v[224:227], v54 offset0:16 offset1:20
	ds_read2_b64 v[246:249], v54 offset0:24 offset1:28
	s_waitcnt lgkmcnt(3)
	v_mfma_f32_16x16x32_bf16 v[26:29], v[26:29], v[10:13], 0
	s_waitcnt lgkmcnt(2)
	v_mfma_f32_16x16x32_bf16 v[26:29], v[50:53], v[14:17], v[26:29]
	s_waitcnt lgkmcnt(1)
	v_mfma_f32_16x16x32_bf16 v[26:29], v[224:227], v[18:21], v[26:29]
	s_waitcnt lgkmcnt(0)
	v_mfma_f32_16x16x32_bf16 v[26:29], v[246:249], v[22:25], v[26:29]
	ds_read_b128 v[50:53], v159
	ds_read_b128 v[54:57], v160
	ds_read_b128 v[58:61], v159 offset:64
	ds_read_b128 v[62:65], v160 offset:64
	s_waitcnt lgkmcnt(3)
	v_mfma_f32_16x16x32_bf16 v[50:53], v[50:53], v[6:9], 0
	s_waitcnt lgkmcnt(2)
	v_mfma_f32_16x16x32_bf16 v[54:57], v[54:57], v[6:9], 0
	s_waitcnt lgkmcnt(1)
	v_mfma_f32_16x16x32_bf16 v[50:53], v[58:61], v[2:5], v[50:53]
	s_waitcnt lgkmcnt(0)
	v_mfma_f32_16x16x32_bf16 v[54:57], v[62:65], v[2:5], v[54:57]
	s_nop 5
	v_fma_f32 v26, v74, v50, v26
	v_fma_f32 v27, v74, v51, v27
	v_pk_fma_f32 v[28:29], v[74:75], v[52:53], v[28:29] op_sel_hi:[0,1,1]
	v_pk_fma_f32 v[72:73], v[76:77], v[54:55], v[26:27] op_sel_hi:[0,1,1]
	v_add_u32_e32 v54, 0x9000, v161
	v_pk_fma_f32 v[70:71], v[76:77], v[56:57], v[28:29] op_sel_hi:[0,1,1]
	ds_read2_b64 v[26:29], v54 offset1:4
	ds_read2_b64 v[50:53], v54 offset0:8 offset1:12
	ds_read2_b64 v[224:227], v54 offset0:16 offset1:20
	ds_read2_b64 v[246:249], v54 offset0:24 offset1:28
	s_waitcnt lgkmcnt(3)
	v_mfma_f32_16x16x32_bf16 v[26:29], v[26:29], v[10:13], 0
	s_waitcnt lgkmcnt(2)
	v_mfma_f32_16x16x32_bf16 v[26:29], v[50:53], v[14:17], v[26:29]
	s_waitcnt lgkmcnt(1)
	v_mfma_f32_16x16x32_bf16 v[26:29], v[224:227], v[18:21], v[26:29]
	s_waitcnt lgkmcnt(0)
	v_mfma_f32_16x16x32_bf16 v[26:29], v[246:249], v[22:25], v[26:29]
	ds_read_b128 v[50:53], v162
	ds_read_b128 v[54:57], v163
	ds_read_b128 v[58:61], v162 offset:64
	ds_read_b128 v[62:65], v163 offset:64
	s_waitcnt lgkmcnt(3)
	v_mfma_f32_16x16x32_bf16 v[50:53], v[50:53], v[6:9], 0
	s_waitcnt lgkmcnt(2)
	v_mfma_f32_16x16x32_bf16 v[54:57], v[54:57], v[6:9], 0
	s_waitcnt lgkmcnt(1)
	v_mfma_f32_16x16x32_bf16 v[50:53], v[58:61], v[2:5], v[50:53]
	s_waitcnt lgkmcnt(0)
	v_mfma_f32_16x16x32_bf16 v[54:57], v[62:65], v[2:5], v[54:57]
	s_nop 5
	v_fma_f32 v26, v74, v50, v26
	v_fma_f32 v27, v74, v51, v27
	v_pk_fma_f32 v[28:29], v[74:75], v[52:53], v[28:29] op_sel_hi:[0,1,1]
	v_pk_fma_f32 v[68:69], v[76:77], v[54:55], v[26:27] op_sel_hi:[0,1,1]
	v_add_u32_e32 v54, 0x9000, v164
	v_pk_fma_f32 v[66:67], v[76:77], v[56:57], v[28:29] op_sel_hi:[0,1,1]
	ds_read2_b64 v[26:29], v54 offset1:4
	ds_read2_b64 v[50:53], v54 offset0:8 offset1:12
	ds_read2_b64 v[224:227], v54 offset0:16 offset1:20
	ds_read2_b64 v[246:249], v54 offset0:24 offset1:28
	s_waitcnt lgkmcnt(3)
	v_mfma_f32_16x16x32_bf16 v[26:29], v[26:29], v[10:13], 0
	s_waitcnt lgkmcnt(2)
	v_mfma_f32_16x16x32_bf16 v[26:29], v[50:53], v[14:17], v[26:29]
	s_waitcnt lgkmcnt(1)
	v_mfma_f32_16x16x32_bf16 v[26:29], v[224:227], v[18:21], v[26:29]
	s_waitcnt lgkmcnt(0)
	v_mfma_f32_16x16x32_bf16 v[26:29], v[246:249], v[22:25], v[26:29]
	ds_read_b128 v[50:53], v165
	ds_read_b128 v[54:57], v166
	ds_read_b128 v[58:61], v165 offset:64
	ds_read_b128 v[62:65], v166 offset:64
	s_waitcnt lgkmcnt(3)
	v_mfma_f32_16x16x32_bf16 v[50:53], v[50:53], v[6:9], 0
	s_waitcnt lgkmcnt(2)
	v_mfma_f32_16x16x32_bf16 v[54:57], v[54:57], v[6:9], 0
	s_waitcnt lgkmcnt(1)
	v_mfma_f32_16x16x32_bf16 v[50:53], v[58:61], v[2:5], v[50:53]
	s_waitcnt lgkmcnt(0)
	v_mfma_f32_16x16x32_bf16 v[54:57], v[62:65], v[2:5], v[54:57]
	s_nop 5
	v_fma_f32 v26, v74, v50, v26
	v_fma_f32 v27, v74, v51, v27
	v_pk_fma_f32 v[28:29], v[74:75], v[52:53], v[28:29] op_sel_hi:[0,1,1]
	v_pk_fma_f32 v[64:65], v[76:77], v[54:55], v[26:27] op_sel_hi:[0,1,1]
	v_add_u32_e32 v54, 0x9000, v167
	v_pk_fma_f32 v[62:63], v[76:77], v[56:57], v[28:29] op_sel_hi:[0,1,1]
	ds_read2_b64 v[26:29], v54 offset1:4
	ds_read2_b64 v[50:53], v54 offset0:8 offset1:12
	ds_read2_b64 v[224:227], v54 offset0:16 offset1:20
	ds_read2_b64 v[246:249], v54 offset0:24 offset1:28
	s_waitcnt lgkmcnt(3)
	v_mfma_f32_16x16x32_bf16 v[26:29], v[26:29], v[10:13], 0
	s_waitcnt lgkmcnt(2)
	v_mfma_f32_16x16x32_bf16 v[26:29], v[50:53], v[14:17], v[26:29]
	s_waitcnt lgkmcnt(1)
	v_mfma_f32_16x16x32_bf16 v[26:29], v[224:227], v[18:21], v[26:29]
	s_waitcnt lgkmcnt(0)
	v_mfma_f32_16x16x32_bf16 v[26:29], v[246:249], v[22:25], v[26:29]
	ds_read_b128 v[50:53], v168
	ds_read_b128 v[54:57], v169
	ds_read_b128 v[58:61], v168 offset:64
	ds_read_b128 v[184:187], v169 offset:64
	s_waitcnt lgkmcnt(3)
	v_mfma_f32_16x16x32_bf16 v[50:53], v[50:53], v[6:9], 0
	s_waitcnt lgkmcnt(2)
	v_mfma_f32_16x16x32_bf16 v[54:57], v[54:57], v[6:9], 0
	s_waitcnt lgkmcnt(1)
	v_mfma_f32_16x16x32_bf16 v[50:53], v[58:61], v[2:5], v[50:53]
	s_waitcnt lgkmcnt(0)
	v_mfma_f32_16x16x32_bf16 v[54:57], v[184:187], v[2:5], v[54:57]
	s_nop 5
	v_fma_f32 v26, v74, v50, v26
	v_fma_f32 v27, v74, v51, v27
	v_pk_fma_f32 v[28:29], v[74:75], v[52:53], v[28:29] op_sel_hi:[0,1,1]
	v_pk_fma_f32 v[60:61], v[76:77], v[54:55], v[26:27] op_sel_hi:[0,1,1]
	v_add_u32_e32 v54, 0x9000, v170
	v_pk_fma_f32 v[58:59], v[76:77], v[56:57], v[28:29] op_sel_hi:[0,1,1]
	ds_read2_b64 v[26:29], v54 offset1:4
	ds_read2_b64 v[50:53], v54 offset0:8 offset1:12
	ds_read2_b64 v[224:227], v54 offset0:16 offset1:20
	ds_read2_b64 v[246:249], v54 offset0:24 offset1:28
	s_waitcnt lgkmcnt(3)
	v_mfma_f32_16x16x32_bf16 v[26:29], v[26:29], v[10:13], 0
	s_waitcnt lgkmcnt(2)
	v_mfma_f32_16x16x32_bf16 v[26:29], v[50:53], v[14:17], v[26:29]
	s_waitcnt lgkmcnt(1)
	v_mfma_f32_16x16x32_bf16 v[26:29], v[224:227], v[18:21], v[26:29]
	s_waitcnt lgkmcnt(0)
	v_mfma_f32_16x16x32_bf16 v[26:29], v[246:249], v[22:25], v[26:29]
	ds_read_b128 v[50:53], v171
	ds_read_b128 v[54:57], v172
	ds_read_b128 v[184:187], v171 offset:64
	ds_read_b128 v[194:197], v172 offset:64
	s_waitcnt lgkmcnt(3)
	v_mfma_f32_16x16x32_bf16 v[50:53], v[50:53], v[6:9], 0
	s_waitcnt lgkmcnt(2)
	v_mfma_f32_16x16x32_bf16 v[54:57], v[54:57], v[6:9], 0
	s_waitcnt lgkmcnt(1)
	v_mfma_f32_16x16x32_bf16 v[50:53], v[184:187], v[2:5], v[50:53]
	s_waitcnt lgkmcnt(0)
	v_mfma_f32_16x16x32_bf16 v[184:187], v[194:197], v[2:5], v[54:57]
	s_nop 5
	v_fma_f32 v26, v74, v50, v26
	v_fma_f32 v27, v74, v51, v27
	v_pk_fma_f32 v[28:29], v[74:75], v[52:53], v[28:29] op_sel_hi:[0,1,1]
	v_pk_fma_f32 v[56:57], v[76:77], v[184:185], v[26:27] op_sel_hi:[0,1,1]
	v_add_u32_e32 v184, 0x9000, v173
	v_pk_fma_f32 v[54:55], v[76:77], v[186:187], v[28:29] op_sel_hi:[0,1,1]
	ds_read2_b64 v[26:29], v184 offset1:4
	ds_read2_b64 v[50:53], v184 offset0:8 offset1:12
	ds_read2_b64 v[224:227], v184 offset0:16 offset1:20
	ds_read2_b64 v[246:249], v184 offset0:24 offset1:28
	s_waitcnt lgkmcnt(3)
	v_mfma_f32_16x16x32_bf16 v[26:29], v[26:29], v[10:13], 0
	s_waitcnt lgkmcnt(2)
	v_mfma_f32_16x16x32_bf16 v[26:29], v[50:53], v[14:17], v[26:29]
	s_waitcnt lgkmcnt(1)
	v_mfma_f32_16x16x32_bf16 v[26:29], v[224:227], v[18:21], v[26:29]
	s_waitcnt lgkmcnt(0)
	v_mfma_f32_16x16x32_bf16 v[26:29], v[246:249], v[22:25], v[26:29]
	ds_read_b128 v[50:53], v174
	ds_read_b128 v[184:187], v175
	ds_read_b128 v[194:197], v174 offset:64
	ds_read_b128 v[198:201], v175 offset:64
	s_waitcnt lgkmcnt(3)
	v_mfma_f32_16x16x32_bf16 v[50:53], v[50:53], v[6:9], 0
	s_waitcnt lgkmcnt(2)
	v_mfma_f32_16x16x32_bf16 v[184:187], v[184:187], v[6:9], 0
	s_waitcnt lgkmcnt(1)
	v_mfma_f32_16x16x32_bf16 v[50:53], v[194:197], v[2:5], v[50:53]
	s_waitcnt lgkmcnt(0)
	v_mfma_f32_16x16x32_bf16 v[184:187], v[198:201], v[2:5], v[184:187]
	s_nop 5
	v_fma_f32 v28, v74, v52, v28
	v_fma_f32 v29, v74, v53, v29
	v_pk_fma_f32 v[26:27], v[74:75], v[50:51], v[26:27] op_sel_hi:[0,1,1]
	v_pk_fma_f32 v[50:51], v[76:77], v[186:187], v[28:29] op_sel_hi:[0,1,1]
	v_pk_fma_f32 v[52:53], v[76:77], v[184:185], v[26:27] op_sel_hi:[0,1,1]
	ds_read2_b64 v[26:29], v188 offset1:4
	ds_read2_b64 v[184:187], v188 offset0:8 offset1:12
	s_waitcnt lgkmcnt(1)
	v_mfma_f32_16x16x32_bf16 v[26:29], v[26:29], v[10:13], 0
	s_waitcnt lgkmcnt(0)
	v_mfma_f32_16x16x32_bf16 v[26:29], v[184:187], v[14:17], v[26:29]
	ds_read2_b64 v[184:187], v188 offset0:16 offset1:20
	s_waitcnt lgkmcnt(0)
	v_mfma_f32_16x16x32_bf16 v[26:29], v[184:187], v[18:21], v[26:29]
	ds_read2_b64 v[184:187], v188 offset0:24 offset1:28
	v_add_u32_e32 v188, 0x9000, v179
	s_waitcnt lgkmcnt(0)
	v_mfma_f32_16x16x32_bf16 v[26:29], v[184:187], v[22:25], v[26:29]
	ds_read_b128 v[184:187], v177
	ds_read_b128 v[194:197], v178
	ds_read_b128 v[198:201], v177 offset:64
	ds_read_b128 v[202:205], v178 offset:64
	s_waitcnt lgkmcnt(3)
	v_mfma_f32_16x16x32_bf16 v[184:187], v[184:187], v[6:9], 0
	s_waitcnt lgkmcnt(2)
	v_mfma_f32_16x16x32_bf16 v[194:197], v[194:197], v[6:9], 0
	s_waitcnt lgkmcnt(1)
	v_mfma_f32_16x16x32_bf16 v[184:187], v[198:201], v[2:5], v[184:187]
	s_waitcnt lgkmcnt(0)
	v_mfma_f32_16x16x32_bf16 v[194:197], v[202:205], v[2:5], v[194:197]
	s_nop 5
	v_fma_f32 v28, v74, v186, v28
	v_fma_f32 v29, v74, v187, v29
	v_pk_fma_f32 v[184:185], v[74:75], v[184:185], v[26:27] op_sel_hi:[0,1,1]
	v_pk_fma_f32 v[26:27], v[76:77], v[196:197], v[28:29] op_sel_hi:[0,1,1]
	v_pk_fma_f32 v[28:29], v[76:77], v[194:195], v[184:185] op_sel_hi:[0,1,1]
	ds_read2_b64 v[184:187], v188 offset1:4
	s_waitcnt lgkmcnt(0)
	v_mfma_f32_16x16x32_bf16 v[10:13], v[184:187], v[10:13], 0
	ds_read2_b64 v[184:187], v188 offset0:8 offset1:12
	s_waitcnt lgkmcnt(0)
	v_mfma_f32_16x16x32_bf16 v[10:13], v[184:187], v[14:17], v[10:13]
	ds_read2_b64 v[14:17], v188 offset0:16 offset1:20
	s_waitcnt lgkmcnt(0)
	v_mfma_f32_16x16x32_bf16 v[10:13], v[14:17], v[18:21], v[10:13]
	ds_read2_b64 v[14:17], v188 offset0:24 offset1:28
	s_waitcnt lgkmcnt(0)
	v_mfma_f32_16x16x32_bf16 v[10:13], v[14:17], v[22:25], v[10:13]
	ds_read_b128 v[14:17], v180
	ds_read_b128 v[18:21], v181
	s_waitcnt lgkmcnt(1)
	v_mfma_f32_16x16x32_bf16 v[14:17], v[14:17], v[6:9], 0
	s_waitcnt lgkmcnt(0)
	v_mfma_f32_16x16x32_bf16 v[6:9], v[18:21], v[6:9], 0
	ds_read_b128 v[18:21], v180 offset:64
	ds_read_b128 v[22:25], v181 offset:64
	s_waitcnt lgkmcnt(1)
	v_mfma_f32_16x16x32_bf16 v[14:17], v[18:21], v[2:5], v[14:17]
	s_waitcnt lgkmcnt(0)
	v_mfma_f32_16x16x32_bf16 v[4:7], v[22:25], v[2:5], v[6:9]
	v_mov_b32_e32 v232, s14
	v_mov_b32_e32 v233, 0
	v_lshlrev_b32_e32 v232, 9, v232
	v_lshl_add_u64 v[232:233], v[34:35], 0, v[232:233]
	global_load_dwordx4 v[22:25], v[232:233], off
	global_load_dwordx4 v[184:187], v[232:233], off offset:64
	global_load_dwordx4 v[194:197], v[232:233], off offset:128
	global_load_dwordx4 v[198:201], v[232:233], off offset:192
	global_load_dwordx4 v[202:205], v[232:233], off offset:256
	global_load_dwordx4 v[224:227], v[232:233], off offset:320
	global_load_dwordx4 v[246:249], v[232:233], off offset:384
	global_load_dwordx4 v[250:253], v[232:233], off offset:448
	s_nop 5
	v_fma_f32 v2, v74, v16, v12
	v_fma_f32 v3, v74, v17, v13
	v_add_f32_e32 v12, v58, v59
	v_mov_b32_e32 v13, v55
	v_pk_fma_f32 v[8:9], v[74:75], v[14:15], v[10:11] op_sel_hi:[0,1,1]
	v_mov_b32_e32 v10, v71
	v_pk_fma_f32 v[2:3], v[76:77], v[6:7], v[2:3] op_sel_hi:[0,1,1]
	v_pk_fma_f32 v[4:5], v[76:77], v[4:5], v[8:9] op_sel_hi:[0,1,1]
	v_mov_b32_e32 v6, v72
	v_mov_b32_e32 v7, v68
	v_mov_b32_e32 v8, v73
	v_mov_b32_e32 v9, v69
	v_pk_add_f32 v[6:7], v[6:7], v[8:9]
	v_mov_b32_e32 v8, v70
	v_mov_b32_e32 v9, v66
	v_mov_b32_e32 v11, v67
	v_pk_add_f32 v[8:9], v[8:9], v[10:11]
	v_mov_b32_e32 v10, v64
	v_pk_add_f32 v[6:7], v[6:7], v[8:9]
	v_pk_mov_b32 v[8:9], v[64:65], v[62:63] op_sel:[1,0]
	v_mov_b32_e32 v11, v63
	v_pk_add_f32 v[8:9], v[8:9], v[10:11]
	v_add_f32_e32 v6, 0, v6
	v_pk_add_f32 v[8:9], v[8:9], v[8:9] op_sel:[0,1] op_sel_hi:[1,0]
	v_add_f32_e32 v6, v6, v7
	v_add_f32_e32 v10, v60, v61
	v_mov_b32_e32 v7, v56
	v_mov_b32_e32 v9, v57
	v_mov_b32_e32 v11, v54
	v_pk_add_f32 v[6:7], v[6:7], v[8:9]
	v_pk_add_f32 v[8:9], v[10:11], v[12:13]
	v_mov_b32_e32 v10, v52
	v_pk_add_f32 v[6:7], v[6:7], v[8:9]
	v_pk_mov_b32 v[8:9], v[52:53], v[50:51] op_sel:[1,0]
	v_mov_b32_e32 v11, v51
	v_pk_add_f32 v[8:9], v[8:9], v[10:11]
	v_pk_add_f32 v[6:7], v[6:7], v[6:7] op_sel:[0,1] op_sel_hi:[1,0]
	v_pk_add_f32 v[8:9], v[8:9], v[8:9] op_sel:[0,1] op_sel_hi:[1,0]
	v_add_f32_e32 v10, v28, v29
	v_add_f32_e32 v12, v26, v27
	v_mov_b32_e32 v7, v4
	v_mov_b32_e32 v9, v5
	v_mov_b32_e32 v11, v2
	v_mov_b32_e32 v13, v3
	v_pk_add_f32 v[6:7], v[6:7], v[8:9]
	v_pk_add_f32 v[8:9], v[10:11], v[12:13]
	s_nop 0
	v_pk_add_f32 v[6:7], v[6:7], v[8:9]
	s_nop 0
	v_add_f32_e32 v6, v6, v7
	ds_bpermute_b32 v7, v80, v6
	s_waitcnt lgkmcnt(0)
	v_add_f32_e32 v6, v6, v7
	ds_bpermute_b32 v7, v81, v6
	s_waitcnt lgkmcnt(0)
	v_add_f32_e32 v14, v6, v7
	v_fmamk_f32 v73, v14, 0xbc000000, v73
	v_fmamk_f32 v69, v14, 0xbc000000, v69
	v_fmamk_f32 v71, v14, 0xbc000000, v71
	v_fmac_f32_e32 v72, 0xbc000000, v14
	v_fmamk_f32 v67, v14, 0xbc000000, v67
	v_fmac_f32_e32 v68, 0xbc000000, v14
	v_mov_b32_e32 v8, v73
	v_mov_b32_e32 v9, v69
	v_fmac_f32_e32 v70, 0xbc000000, v14
	v_fmac_f32_e32 v66, 0xbc000000, v14
	v_mov_b32_e32 v6, v72
	v_mov_b32_e32 v7, v68
	v_pk_mul_f32 v[8:9], v[8:9], v[8:9]
	v_mov_b32_e32 v10, v71
	v_mov_b32_e32 v11, v67
	v_pk_fma_f32 v[6:7], v[6:7], v[6:7], v[8:9]
	v_mov_b32_e32 v8, v70
	v_mov_b32_e32 v9, v66
	v_pk_mul_f32 v[10:11], v[10:11], v[10:11]
	v_fmamk_f32 v65, v14, 0xbc000000, v65
	v_pk_fma_f32 v[8:9], v[8:9], v[8:9], v[10:11]
	v_fmac_f32_e32 v64, 0xbc000000, v14
	v_pk_add_f32 v[6:7], v[6:7], v[8:9]
	v_fmamk_f32 v63, v14, 0xbc000000, v63
	v_fmac_f32_e32 v62, 0xbc000000, v14
	v_pk_add_f32 v[6:7], v[6:7], v[6:7] op_sel_hi:[0,1]
	v_pk_mul_f32 v[8:9], v[62:63], v[62:63]
	v_pk_mul_f32 v[10:11], v[64:65], v[64:65]
	v_fmac_f32_e32 v60, 0xbc000000, v14
	v_pk_mov_b32 v[12:13], v[10:11], v[8:9] op_sel:[1,0]
	v_mov_b32_e32 v11, v9
	v_fmamk_f32 v61, v14, 0xbc000000, v61
	v_fmac_f32_e32 v58, 0xbc000000, v14
	v_mul_f32_e32 v6, v60, v60
	v_pk_add_f32 v[8:9], v[12:13], v[10:11]
	v_fmamk_f32 v59, v14, 0xbc000000, v59
	v_pk_fma_f32 v[10:11], v[60:61], v[60:61], v[6:7] op_sel_hi:[1,1,0]
	v_mul_f32_e32 v6, v58, v58
	v_pk_add_f32 v[8:9], v[8:9], v[8:9] op_sel_hi:[0,1]
	v_pk_fma_f32 v[12:13], v[58:59], v[58:59], v[6:7] op_sel_hi:[1,1,0]
	v_fmamk_f32 v55, v14, 0xbc000000, v55
	v_fmac_f32_e32 v54, 0xbc000000, v14
	v_fmamk_f32 v57, v14, 0xbc000000, v57
	v_fmac_f32_e32 v56, 0xbc000000, v14
	v_mul_f32_e32 v10, v56, v56
	v_mul_f32_e32 v12, v57, v57
	v_mul_f32_e32 v8, v54, v54
	v_mul_f32_e32 v6, v55, v55
	v_pk_add_f32 v[10:11], v[10:11], v[12:13]
	v_pk_add_f32 v[6:7], v[8:9], v[6:7]
	v_fmamk_f32 v53, v14, 0xbc000000, v53
	v_pk_add_f32 v[6:7], v[10:11], v[6:7]
	v_fmac_f32_e32 v52, 0xbc000000, v14
	v_fmamk_f32 v51, v14, 0xbc000000, v51
	v_fmac_f32_e32 v50, 0xbc000000, v14
	v_pk_add_f32 v[6:7], v[6:7], v[6:7] op_sel_hi:[0,1]
	v_pk_mul_f32 v[8:9], v[50:51], v[50:51]
	v_pk_mul_f32 v[10:11], v[52:53], v[52:53]
	v_fmac_f32_e32 v28, 0xbc000000, v14
	v_pk_mov_b32 v[12:13], v[10:11], v[8:9] op_sel:[1,0]
	v_mov_b32_e32 v11, v9
	v_fmamk_f32 v29, v14, 0xbc000000, v29
	v_fmac_f32_e32 v26, 0xbc000000, v14
	v_mul_f32_e32 v6, v28, v28
	v_pk_add_f32 v[8:9], v[12:13], v[10:11]
	v_fmamk_f32 v27, v14, 0xbc000000, v27
	v_pk_fma_f32 v[10:11], v[28:29], v[28:29], v[6:7] op_sel_hi:[1,1,0]
	v_mul_f32_e32 v6, v26, v26
	v_pk_add_f32 v[8:9], v[8:9], v[8:9] op_sel_hi:[0,1]
	v_pk_fma_f32 v[12:13], v[26:27], v[26:27], v[6:7] op_sel_hi:[1,1,0]
	v_fmamk_f32 v3, v14, 0xbc000000, v3
	v_fmac_f32_e32 v2, 0xbc000000, v14
	v_fmamk_f32 v5, v14, 0xbc000000, v5
	v_fmac_f32_e32 v4, 0xbc000000, v14
	v_mul_f32_e32 v10, v4, v4
	v_mul_f32_e32 v12, v5, v5
	v_mul_f32_e32 v8, v2, v2
	v_mul_f32_e32 v6, v3, v3
	v_pk_add_f32 v[10:11], v[10:11], v[12:13]
	v_pk_add_f32 v[6:7], v[8:9], v[6:7]
	s_nop 0
	v_pk_add_f32 v[6:7], v[10:11], v[6:7]
	s_nop 0
	v_add_f32_e32 v6, v6, v7
	ds_bpermute_b32 v7, v80, v6
	s_waitcnt lgkmcnt(0)
	v_add_f32_e32 v6, v6, v7
	ds_bpermute_b32 v7, v81, v6
	s_waitcnt lgkmcnt(0)
	v_add_f32_e32 v6, v6, v7
	v_fmamk_f32 v6, v6, 0x3c000000, v223
	v_cmp_gt_f32_e32 vcc, s74, v6
	v_mul_f32_e32 v7, 0x4f800000, v6
	s_nop 0
	v_cndmask_b32_e32 v6, v6, v7, vcc
	v_sqrt_f32_e32 v7, v6
	s_nop 0
	v_add_u32_e32 v8, -1, v7
	v_fma_f32 v9, -v8, v7, v6
	v_cmp_ge_f32_e64 s[74:75], 0, v9
	v_add_u32_e32 v9, 1, v7
	s_nop 0
	v_cndmask_b32_e64 v8, v7, v8, s[74:75]
	v_fma_f32 v7, -v9, v7, v6
	v_cmp_lt_f32_e64 s[74:75], 0, v7
	s_nop 1
	v_cndmask_b32_e64 v7, v8, v9, s[74:75]
	v_mul_f32_e32 v8, 0x37800000, v7
	v_cndmask_b32_e32 v7, v7, v8, vcc
	v_mov_b32_e32 v8, 0x260
	v_cmp_class_f32_e32 vcc, v6, v8
	s_nop 1
	v_cndmask_b32_e32 v6, v7, v6, vcc
	v_div_scale_f32 v7, s[74:75], v6, v6, 1.0
	v_rcp_f32_e32 v8, v7
	s_nop 0
	v_fma_f32 v9, -v7, v8, 1.0
	v_fmac_f32_e32 v8, v9, v8
	v_div_scale_f32 v9, vcc, 1.0, v6, 1.0
	v_mul_f32_e32 v10, v9, v8
	v_fma_f32 v11, -v7, v10, v9
	v_fmac_f32_e32 v10, v11, v8
	v_fma_f32 v7, -v7, v10, v9
	v_div_fmas_f32 v7, v7, v8, v10
	v_add_u32_e32 v8, s15, v77
	v_ashrrev_i32_e32 v9, 31, v8
	v_lshlrev_b64 v[8:9], 10, v[8:9]
	v_lshl_add_u64 v[8:9], s[72:73], 0, v[8:9]
	v_lshl_add_u64 v[8:9], v[8:9], 0, s[84:85]
	v_lshl_add_u64 v[8:9], v[8:9], 0, v[0:1]
	s_lshl_b32 s84, s14, 9
	v_lshl_add_u64 v[10:11], v[34:35], 0, s[84:85]
	s_waitcnt vmcnt(0)
	v_mov_b64_e32 v[16:17], v[206:207]
	v_mov_b64_e32 v[12:13], v[22:23]
	v_mov_b64_e32 v[14:15], v[24:25]
	v_div_fixup_f32 v6, v7, v6, 1.0
	v_pk_mul_f32 v[18:19], v[72:73], v[6:7] op_sel_hi:[1,0]
	v_pk_mul_f32 v[20:21], v[70:71], v[6:7] op_sel_hi:[1,0]
	s_cmpk_lt_i32 s81, 0x600
	v_pk_mul_f32 v[12:13], v[12:13], v[18:19]
	v_lshlrev_b32_e32 v18, 16, v16
	v_mul_f32_e32 v7, 0xbfb8aa3b, v18
	v_exp_f32_e32 v7, v7
	v_and_b32_e32 v19, 0xffff0000, v16
	v_pk_mul_f32 v[14:15], v[14:15], v[20:21]
	v_lshlrev_b32_e32 v16, 16, v17
	v_add_f32_e32 v7, 1.0, v7
	v_rcp_f32_e32 v20, v7
	v_mul_f32_e32 v7, 0xbfb8aa3b, v19
	v_exp_f32_e32 v7, v7
	v_and_b32_e32 v17, 0xffff0000, v17
	v_add_f32_e32 v7, 1.0, v7
	v_rcp_f32_e32 v21, v7
	v_mul_f32_e32 v7, 0xbfb8aa3b, v16
	v_exp_f32_e32 v7, v7
	v_pk_mul_f32 v[18:19], v[20:21], v[18:19]
	s_nop 0
	v_pk_mul_f32 v[12:13], v[18:19], v[12:13]
	v_add_f32_e32 v7, 1.0, v7
	v_rcp_f32_e32 v18, v7
	v_mul_f32_e32 v7, 0xbfb8aa3b, v17
	v_exp_f32_e32 v7, v7
	v_cvt_pk_bf16_f32 v12, v12, v13
	v_add_f32_e32 v7, 1.0, v7
	v_rcp_f32_e32 v19, v7
	v_pk_mul_f32 v[20:21], v[66:67], v[6:7] op_sel_hi:[1,0]
	v_pk_mul_f32 v[16:17], v[18:19], v[16:17]
	s_nop 0
	v_pk_mul_f32 v[14:15], v[16:17], v[14:15]
	v_pk_mul_f32 v[18:19], v[68:69], v[6:7] op_sel_hi:[1,0]
	v_cvt_pk_bf16_f32 v13, v14, v15
	global_store_dwordx2 v[8:9], v[12:13], off
	v_mov_b64_e32 v[16:17], v[208:209]
	v_mov_b64_e32 v[12:13], v[184:185]
	v_mov_b64_e32 v[14:15], v[186:187]
	v_pk_mul_f32 v[12:13], v[12:13], v[18:19]
	v_lshlrev_b32_e32 v18, 16, v16
	v_mul_f32_e32 v7, 0xbfb8aa3b, v18
	v_exp_f32_e32 v7, v7
	v_and_b32_e32 v19, 0xffff0000, v16
	v_pk_mul_f32 v[14:15], v[14:15], v[20:21]
	v_lshlrev_b32_e32 v16, 16, v17
	v_add_f32_e32 v7, 1.0, v7
	v_rcp_f32_e32 v20, v7
	v_mul_f32_e32 v7, 0xbfb8aa3b, v19
	v_exp_f32_e32 v7, v7
	v_and_b32_e32 v17, 0xffff0000, v17
	v_add_f32_e32 v7, 1.0, v7
	v_rcp_f32_e32 v21, v7
	v_mul_f32_e32 v7, 0xbfb8aa3b, v16
	v_exp_f32_e32 v7, v7
	v_pk_mul_f32 v[18:19], v[20:21], v[18:19]
	s_nop 0
	v_pk_mul_f32 v[12:13], v[18:19], v[12:13]
	v_add_f32_e32 v7, 1.0, v7
	v_rcp_f32_e32 v18, v7
	v_mul_f32_e32 v7, 0xbfb8aa3b, v17
	v_exp_f32_e32 v7, v7
	v_cvt_pk_bf16_f32 v12, v12, v13
	v_add_f32_e32 v7, 1.0, v7
	v_rcp_f32_e32 v19, v7
	v_pk_mul_f32 v[20:21], v[62:63], v[6:7] op_sel_hi:[1,0]
	v_pk_mul_f32 v[16:17], v[18:19], v[16:17]
	s_nop 0
	v_pk_mul_f32 v[14:15], v[16:17], v[14:15]
	v_pk_mul_f32 v[18:19], v[64:65], v[6:7] op_sel_hi:[1,0]
	v_cvt_pk_bf16_f32 v13, v14, v15
	global_store_dwordx2 v[8:9], v[12:13], off offset:32
	v_mov_b64_e32 v[16:17], v[210:211]
	v_mov_b64_e32 v[12:13], v[194:195]
	v_mov_b64_e32 v[14:15], v[196:197]
	v_pk_mul_f32 v[12:13], v[12:13], v[18:19]
	v_lshlrev_b32_e32 v18, 16, v16
	v_mul_f32_e32 v7, 0xbfb8aa3b, v18
	v_exp_f32_e32 v7, v7
	v_and_b32_e32 v19, 0xffff0000, v16
	v_pk_mul_f32 v[14:15], v[14:15], v[20:21]
	v_lshlrev_b32_e32 v16, 16, v17
	v_add_f32_e32 v7, 1.0, v7
	v_rcp_f32_e32 v20, v7
	v_mul_f32_e32 v7, 0xbfb8aa3b, v19
	v_exp_f32_e32 v7, v7
	v_and_b32_e32 v17, 0xffff0000, v17
	v_add_f32_e32 v7, 1.0, v7
	v_rcp_f32_e32 v21, v7
	v_mul_f32_e32 v7, 0xbfb8aa3b, v16
	v_exp_f32_e32 v7, v7
	v_pk_mul_f32 v[18:19], v[20:21], v[18:19]
	s_nop 0
	v_pk_mul_f32 v[12:13], v[18:19], v[12:13]
	v_add_f32_e32 v7, 1.0, v7
	v_rcp_f32_e32 v18, v7
	v_mul_f32_e32 v7, 0xbfb8aa3b, v17
	v_exp_f32_e32 v7, v7
	v_cvt_pk_bf16_f32 v12, v12, v13
	v_add_f32_e32 v7, 1.0, v7
	v_rcp_f32_e32 v19, v7
	v_pk_mul_f32 v[20:21], v[58:59], v[6:7] op_sel_hi:[1,0]
	v_pk_mul_f32 v[16:17], v[18:19], v[16:17]
	s_nop 0
	v_pk_mul_f32 v[14:15], v[16:17], v[14:15]
	v_pk_mul_f32 v[18:19], v[60:61], v[6:7] op_sel_hi:[1,0]
	v_cvt_pk_bf16_f32 v13, v14, v15
	global_store_dwordx2 v[8:9], v[12:13], off offset:64
	v_mov_b64_e32 v[12:13], v[212:213]
	v_mov_b64_e32 v[14:15], v[198:199]
	v_mov_b64_e32 v[16:17], v[200:201]
	v_pk_mul_f32 v[14:15], v[14:15], v[18:19]
	v_lshlrev_b32_e32 v18, 16, v12
	v_mul_f32_e32 v7, 0xbfb8aa3b, v18
	v_exp_f32_e32 v7, v7
	v_and_b32_e32 v19, 0xffff0000, v12
	v_pk_mul_f32 v[16:17], v[16:17], v[20:21]
	v_add_f32_e32 v7, 1.0, v7
	v_rcp_f32_e32 v20, v7
	v_mul_f32_e32 v7, 0xbfb8aa3b, v19
	v_exp_f32_e32 v7, v7
	s_nop 0
	v_add_f32_e32 v7, 1.0, v7
	v_rcp_f32_e32 v21, v7
	s_nop 0
	v_pk_mul_f32 v[18:19], v[20:21], v[18:19]
	s_nop 0
	v_pk_mul_f32 v[14:15], v[18:19], v[14:15]
	s_nop 0
	v_cvt_pk_bf16_f32 v12, v14, v15
	v_lshlrev_b32_e32 v14, 16, v13
	v_mul_f32_e32 v7, 0xbfb8aa3b, v14
	v_exp_f32_e32 v7, v7
	v_and_b32_e32 v15, 0xffff0000, v13
	v_add_f32_e32 v7, 1.0, v7
	v_rcp_f32_e32 v18, v7
	v_mul_f32_e32 v7, 0xbfb8aa3b, v15
	v_exp_f32_e32 v7, v7
	s_nop 0
	v_add_f32_e32 v7, 1.0, v7
	v_rcp_f32_e32 v19, v7
	v_pk_mul_f32 v[20:21], v[54:55], v[6:7] op_sel_hi:[1,0]
	v_pk_mul_f32 v[14:15], v[18:19], v[14:15]
	s_nop 0
	v_pk_mul_f32 v[14:15], v[14:15], v[16:17]
	v_pk_mul_f32 v[18:19], v[56:57], v[6:7] op_sel_hi:[1,0]
	v_cvt_pk_bf16_f32 v13, v14, v15
	global_store_dwordx2 v[8:9], v[12:13], off offset:96
	v_mov_b64_e32 v[16:17], v[214:215]
	v_mov_b64_e32 v[12:13], v[202:203]
	v_mov_b64_e32 v[14:15], v[204:205]
	v_pk_mul_f32 v[12:13], v[12:13], v[18:19]
	v_lshlrev_b32_e32 v18, 16, v16
	v_mul_f32_e32 v7, 0xbfb8aa3b, v18
	v_exp_f32_e32 v7, v7
	v_and_b32_e32 v19, 0xffff0000, v16
	v_pk_mul_f32 v[14:15], v[14:15], v[20:21]
	v_lshlrev_b32_e32 v16, 16, v17
	v_add_f32_e32 v7, 1.0, v7
	v_rcp_f32_e32 v20, v7
	v_mul_f32_e32 v7, 0xbfb8aa3b, v19
	v_exp_f32_e32 v7, v7
	v_and_b32_e32 v17, 0xffff0000, v17
	v_add_f32_e32 v7, 1.0, v7
	v_rcp_f32_e32 v21, v7
	v_mul_f32_e32 v7, 0xbfb8aa3b, v16
	v_exp_f32_e32 v7, v7
	v_pk_mul_f32 v[18:19], v[20:21], v[18:19]
	s_nop 0
	v_pk_mul_f32 v[12:13], v[18:19], v[12:13]
	v_add_f32_e32 v7, 1.0, v7
	v_rcp_f32_e32 v18, v7
	v_mul_f32_e32 v7, 0xbfb8aa3b, v17
	v_exp_f32_e32 v7, v7
	v_cvt_pk_bf16_f32 v12, v12, v13
	v_add_f32_e32 v7, 1.0, v7
	v_rcp_f32_e32 v19, v7
	v_pk_mul_f32 v[20:21], v[50:51], v[6:7] op_sel_hi:[1,0]
	v_pk_mul_f32 v[16:17], v[18:19], v[16:17]
	s_nop 0
	v_pk_mul_f32 v[14:15], v[16:17], v[14:15]
	v_pk_mul_f32 v[18:19], v[52:53], v[6:7] op_sel_hi:[1,0]
	v_cvt_pk_bf16_f32 v13, v14, v15
	global_store_dwordx2 v[8:9], v[12:13], off offset:128
	v_mov_b64_e32 v[16:17], v[216:217]
	v_mov_b64_e32 v[12:13], v[224:225]
	v_mov_b64_e32 v[14:15], v[226:227]
	v_pk_mul_f32 v[12:13], v[12:13], v[18:19]
	v_lshlrev_b32_e32 v18, 16, v16
	v_mul_f32_e32 v7, 0xbfb8aa3b, v18
	v_exp_f32_e32 v7, v7
	v_and_b32_e32 v19, 0xffff0000, v16
	v_pk_mul_f32 v[14:15], v[14:15], v[20:21]
	v_lshlrev_b32_e32 v16, 16, v17
	v_add_f32_e32 v7, 1.0, v7
	v_rcp_f32_e32 v20, v7
	v_mul_f32_e32 v7, 0xbfb8aa3b, v19
	v_exp_f32_e32 v7, v7
	v_and_b32_e32 v17, 0xffff0000, v17
	v_add_f32_e32 v7, 1.0, v7
	v_rcp_f32_e32 v21, v7
	v_mul_f32_e32 v7, 0xbfb8aa3b, v16
	v_exp_f32_e32 v7, v7
	v_pk_mul_f32 v[18:19], v[20:21], v[18:19]
	s_nop 0
	v_pk_mul_f32 v[12:13], v[18:19], v[12:13]
	v_add_f32_e32 v7, 1.0, v7
	v_rcp_f32_e32 v18, v7
	v_mul_f32_e32 v7, 0xbfb8aa3b, v17
	v_exp_f32_e32 v7, v7
	v_cvt_pk_bf16_f32 v12, v12, v13
	v_add_f32_e32 v7, 1.0, v7
	v_rcp_f32_e32 v19, v7
	v_pk_mul_f32 v[20:21], v[26:27], v[6:7] op_sel_hi:[1,0]
	v_pk_mul_f32 v[16:17], v[18:19], v[16:17]
	s_nop 0
	v_pk_mul_f32 v[14:15], v[16:17], v[14:15]
	v_pk_mul_f32 v[18:19], v[28:29], v[6:7] op_sel_hi:[1,0]
	v_cvt_pk_bf16_f32 v13, v14, v15
	global_store_dwordx2 v[8:9], v[12:13], off offset:160
	v_mov_b64_e32 v[16:17], v[218:219]
	v_mov_b64_e32 v[12:13], v[246:247]
	v_mov_b64_e32 v[14:15], v[248:249]
	v_pk_mul_f32 v[12:13], v[12:13], v[18:19]
	v_lshlrev_b32_e32 v18, 16, v16
	v_mul_f32_e32 v7, 0xbfb8aa3b, v18
	v_exp_f32_e32 v7, v7
	v_and_b32_e32 v19, 0xffff0000, v16
	v_pk_mul_f32 v[14:15], v[14:15], v[20:21]
	v_lshlrev_b32_e32 v16, 16, v17
	v_add_f32_e32 v7, 1.0, v7
	v_rcp_f32_e32 v20, v7
	v_mul_f32_e32 v7, 0xbfb8aa3b, v19
	v_exp_f32_e32 v7, v7
	v_and_b32_e32 v17, 0xffff0000, v17
	v_add_f32_e32 v7, 1.0, v7
	v_rcp_f32_e32 v21, v7
	v_mul_f32_e32 v7, 0xbfb8aa3b, v16
	v_exp_f32_e32 v7, v7
	v_pk_mul_f32 v[18:19], v[20:21], v[18:19]
	s_nop 0
	v_pk_mul_f32 v[12:13], v[18:19], v[12:13]
	v_add_f32_e32 v7, 1.0, v7
	v_rcp_f32_e32 v18, v7
	v_mul_f32_e32 v7, 0xbfb8aa3b, v17
	v_exp_f32_e32 v7, v7
	v_cvt_pk_bf16_f32 v12, v12, v13
	v_add_f32_e32 v7, 1.0, v7
	v_rcp_f32_e32 v19, v7
	v_pk_mul_f32 v[4:5], v[4:5], v[6:7] op_sel_hi:[1,0]
	v_pk_mul_f32 v[2:3], v[2:3], v[6:7] op_sel_hi:[1,0]
	v_pk_mul_f32 v[16:17], v[18:19], v[16:17]
	s_nop 0
	v_pk_mul_f32 v[14:15], v[16:17], v[14:15]
	s_nop 0
	v_cvt_pk_bf16_f32 v13, v14, v15
	global_store_dwordx2 v[8:9], v[12:13], off offset:192
	v_mov_b64_e32 v[12:13], v[220:221]
	v_mov_b64_e32 v[14:15], v[250:251]
	v_mov_b64_e32 v[16:17], v[252:253]
	v_lshlrev_b32_e32 v6, 16, v12
	v_and_b32_e32 v7, 0xffff0000, v12
	v_mul_f32_e32 v10, 0xbfb8aa3b, v6
	v_mul_f32_e32 v11, 0xbfb8aa3b, v7
	v_exp_f32_e32 v10, v10
	v_exp_f32_e32 v11, v11
	v_pk_mul_f32 v[4:5], v[14:15], v[4:5]
	v_pk_mul_f32 v[2:3], v[16:17], v[2:3]
	v_add_f32_e32 v10, 1.0, v10
	v_add_f32_e32 v11, 1.0, v11
	v_rcp_f32_e32 v10, v10
	v_rcp_f32_e32 v11, v11
	s_nop 0
	v_pk_mul_f32 v[6:7], v[10:11], v[6:7]
	s_nop 0
	v_pk_mul_f32 v[4:5], v[4:5], v[6:7]
	v_lshlrev_b32_e32 v6, 16, v13
	v_cvt_pk_bf16_f32 v4, v4, v5
	v_mul_f32_e32 v5, 0xbfb8aa3b, v6
	v_exp_f32_e32 v5, v5
	v_and_b32_e32 v7, 0xffff0000, v13
	v_add_f32_e32 v5, 1.0, v5
	v_rcp_f32_e32 v10, v5
	v_mul_f32_e32 v5, 0xbfb8aa3b, v7
	v_exp_f32_e32 v5, v5
	s_nop 0
	v_add_f32_e32 v5, 1.0, v5
	v_rcp_f32_e32 v11, v5
	s_nop 0
	v_pk_mul_f32 v[6:7], v[10:11], v[6:7]
	s_nop 0
	v_pk_mul_f32 v[2:3], v[2:3], v[6:7]
	s_nop 0
	v_cvt_pk_bf16_f32 v5, v2, v3
	global_store_dwordx2 v[8:9], v[4:5], off offset:224
	s_barrier
	s_cbranch_scc1 .LBB0_174
	v_readlane_b32 s96, v255, 10
	v_readlane_b32 s97, v255, 11
	v_readlane_b32 s74, v255, 8
	v_readlane_b32 s2, v255, 13
	v_readlane_b32 s75, v255, 9
	v_readlane_b32 s97, v255, 12
	v_readlane_b32 s93, v255, 19

.LBB0_198:
	v_add_u32_e32 v0, s8, v206
	ds_read_b64_tr_b16 v[178:179], v0 offset:24576
	ds_read_b64_tr_b16 v[180:181], v0 offset:25088
	s_waitcnt lgkmcnt(9)
	v_mfma_f32_32x32x16_bf16 v[98:113], v[174:177], v[138:141], v[34:49]
	v_add_f32_e32 v82, v66, v67
	v_add_f32_e32 v82, v68, v82
	v_add_f32_e32 v82, v69, v82
	v_add_f32_e32 v82, v70, v82
	v_add_f32_e32 v82, v71, v82
	v_cvt_pk_bf16_f32 v142, v66, v67
	v_cvt_pk_bf16_f32 v143, v68, v69
	ds_read_b64_tr_b16 v[174:175], v0 offset:28672
	ds_read_b64_tr_b16 v[176:177], v0 offset:29184
	v_add_f32_e32 v66, v72, v82
	s_waitcnt lgkmcnt(10)
	v_mfma_f32_32x32x16_bf16 v[82:97], v[170:173], v[138:141], v[34:49]
	v_add_f32_e32 v66, v73, v66
	v_add_f32_e32 v66, v74, v66
	v_add_f32_e32 v122, v75, v66
	v_cvt_pk_bf16_f32 v144, v70, v71
	v_cvt_pk_bf16_f32 v145, v72, v73
	ds_read_b64_tr_b16 v[66:67], v0 offset:25600
	ds_read_b64_tr_b16 v[68:69], v0 offset:26112
	s_waitcnt lgkmcnt(11)
	v_mfma_f32_32x32x16_bf16 v[98:113], v[166:169], v[126:129], v[98:113]
	v_add_f32_e32 v70, v76, v122
	v_add_f32_e32 v70, v77, v70
	v_add_f32_e32 v70, v78, v70
	v_add_f32_e32 v122, v79, v70
	v_cvt_pk_bf16_f32 v134, v74, v75
	v_cvt_pk_bf16_f32 v135, v76, v77
	ds_read_b64_tr_b16 v[70:71], v0 offset:29696
	ds_read_b64_tr_b16 v[72:73], v0 offset:30208
	s_waitcnt lgkmcnt(12)
	v_mfma_f32_32x32x16_bf16 v[82:97], v[162:165], v[126:129], v[82:97]
	v_add_f32_e32 v74, v80, v122
	v_add_f32_e32 v74, v81, v74
	v_add_f32_e32 v74, v50, v74
	v_add_f32_e32 v122, v51, v74
	v_cvt_pk_bf16_f32 v136, v78, v79
	v_cvt_pk_bf16_f32 v137, v80, v81
	ds_read_b64_tr_b16 v[74:75], v0 offset:26624
	ds_read_b64_tr_b16 v[76:77], v0 offset:27136
	s_waitcnt lgkmcnt(13)
	v_mfma_f32_32x32x16_bf16 v[98:113], v[158:161], v[118:121], v[98:113]
	v_add_f32_e32 v78, v52, v122
	v_add_f32_e32 v78, v53, v78
	v_add_f32_e32 v78, v54, v78
	v_add_f32_e32 v78, v55, v78
	v_cvt_pk_bf16_f32 v130, v50, v51
	v_cvt_pk_bf16_f32 v131, v52, v53
	ds_read_b64_tr_b16 v[50:51], v0 offset:30720
	ds_read_b64_tr_b16 v[52:53], v0 offset:31232
	s_waitcnt lgkmcnt(14)
	v_mfma_f32_32x32x16_bf16 v[82:97], v[154:157], v[118:121], v[82:97]
	v_add_f32_e32 v78, v56, v78
	v_add_f32_e32 v78, v57, v78
	v_add_f32_e32 v78, v58, v78
	v_add_f32_e32 v78, v59, v78
	v_cvt_pk_bf16_f32 v132, v54, v55
	v_cvt_pk_bf16_f32 v133, v56, v57
	ds_read_b64_tr_b16 v[54:55], v0 offset:27648
	ds_read_b64_tr_b16 v[56:57], v0 offset:28160
	s_waitcnt lgkmcnt(14)
	v_mfma_f32_32x32x16_bf16 v[98:113], v[150:153], v[114:117], v[98:113]
	v_add_f32_e32 v78, v60, v78
	v_add_f32_e32 v78, v61, v78
	v_add_f32_e32 v78, v62, v78
	v_add_f32_e32 v78, v63, v78
	v_cvt_pk_bf16_f32 v122, v58, v59
	v_cvt_pk_bf16_f32 v123, v60, v61
	ds_read_b64_tr_b16 v[58:59], v0 offset:31744
	ds_read_b64_tr_b16 v[60:61], v0 offset:32256
	v_mfma_f32_32x32x16_bf16 v[82:97], v[146:149], v[114:117], v[82:97]
	v_add_f32_e32 v0, v64, v78
	v_add_f32_e32 v0, v65, v0
	v_cvt_pk_bf16_f32 v124, v62, v63
	v_cvt_pk_bf16_f32 v125, v64, v65
	s_add_i32 s8, s21, s40
	s_mov_b32 m0, s8
	v_lshl_add_u64 v[62:63], v[184:185], 0, s[98:99]
	global_load_lds_dwordx4 v[62:63], off
	s_add_i32 s8, s18, s41
	s_mov_b32 m0, s8
	v_lshl_add_u64 v[62:63], v[182:183], 0, s[98:99]
	global_load_lds_dwordx4 v[62:63], off
	v_max_f32_e32 v62, v98, v99
	v_max3_f32 v63, v100, v101, v83
	v_max3_f32 v62, v62, v82, v84
	v_max3_f32 v62, v62, v85, v102
	v_max3_f32 v63, v63, v104, v105
	v_max3_f32 v62, v62, v103, v86
	v_max3_f32 v63, v63, v88, v89
	v_max3_f32 v62, v62, v87, v106
	v_max3_f32 v63, v63, v108, v109
	v_max3_f32 v62, v62, v107, v90
	v_max3_f32 v63, v63, v92, v93
	v_max3_f32 v62, v62, v91, v110
	v_max3_f32 v63, v63, v112, v113
	v_max3_f32 v62, v62, v111, v94
	v_max3_f32 v63, v63, v96, v97
	v_max3_f32 v62, v62, v95, v63
	v_mov_b32_e32 v63, v62
	s_nop 1
	v_permlane32_swap_b32_e32 v62, v63
	v_max_f32_e32 v62, v62, v63
	v_cmp_lt_f32_e32 vcc, s91, v62
	s_cmp_lg_u64 vcc, 0
	v_add_f32_e32 v0, v208, v0
	s_cselect_b64 s[8:9], -1, 0
	s_cbranch_vccnz .LBB0_206

.LBB0_201:
	s_add_i32 s8, s18, 0x2000
	s_cmpk_lg_i32 s18, 0x4000
	s_cselect_b32 s44, s8, 0
	v_add_u32_e32 v186, s21, v206
	ds_read_b64_tr_b16 v[150:151], v186 offset:24576
	ds_read_b64_tr_b16 v[152:153], v186 offset:25088
	s_waitcnt lgkmcnt(9)
	v_mfma_f32_32x32x16_bf16 v[66:81], v[62:65], v[138:141], v[34:49]
	v_add_f32_e32 v50, v98, v99
	v_add_f32_e32 v50, v100, v50
	v_add_f32_e32 v50, v101, v50
	v_add_f32_e32 v50, v102, v50
	v_add_f32_e32 v50, v103, v50
	v_cvt_pk_bf16_f32 v142, v98, v99
	v_cvt_pk_bf16_f32 v143, v100, v101
	ds_read_b64_tr_b16 v[146:147], v186 offset:28672
	ds_read_b64_tr_b16 v[148:149], v186 offset:29184
	v_add_f32_e32 v50, v104, v50
	v_add_f32_e32 v50, v105, v50
	v_add_f32_e32 v50, v106, v50
	v_add_f32_e32 v122, v107, v50
	s_waitcnt lgkmcnt(10)
	v_mfma_f32_32x32x16_bf16 v[50:65], v[174:177], v[138:141], v[34:49]
	v_cvt_pk_bf16_f32 v144, v102, v103
	v_cvt_pk_bf16_f32 v145, v104, v105
	ds_read_b64_tr_b16 v[98:99], v186 offset:25600
	ds_read_b64_tr_b16 v[100:101], v186 offset:26112
	s_waitcnt lgkmcnt(11)
	v_mfma_f32_32x32x16_bf16 v[66:81], v[178:181], v[126:129], v[66:81]
	v_add_f32_e32 v102, v108, v122
	v_add_f32_e32 v102, v109, v102
	v_add_f32_e32 v102, v110, v102
	v_add_f32_e32 v122, v111, v102
	v_cvt_pk_bf16_f32 v134, v106, v107
	v_cvt_pk_bf16_f32 v135, v108, v109
	ds_read_b64_tr_b16 v[102:103], v186 offset:29696
	ds_read_b64_tr_b16 v[104:105], v186 offset:30208
	s_waitcnt lgkmcnt(12)
	v_mfma_f32_32x32x16_bf16 v[50:65], v[170:173], v[126:129], v[50:65]
	v_add_f32_e32 v106, v112, v122
	v_add_f32_e32 v106, v113, v106
	v_add_f32_e32 v106, v82, v106
	v_add_f32_e32 v122, v83, v106
	v_cvt_pk_bf16_f32 v136, v110, v111
	v_cvt_pk_bf16_f32 v137, v112, v113
	ds_read_b64_tr_b16 v[106:107], v186 offset:26624
	ds_read_b64_tr_b16 v[108:109], v186 offset:27136
	s_waitcnt lgkmcnt(13)
	v_mfma_f32_32x32x16_bf16 v[66:81], v[166:169], v[118:121], v[66:81]
	v_add_f32_e32 v110, v84, v122
	v_add_f32_e32 v110, v85, v110
	v_add_f32_e32 v110, v86, v110
	v_add_f32_e32 v110, v87, v110
	v_cvt_pk_bf16_f32 v130, v82, v83
	v_cvt_pk_bf16_f32 v131, v84, v85
	ds_read_b64_tr_b16 v[82:83], v186 offset:30720
	ds_read_b64_tr_b16 v[84:85], v186 offset:31232
	s_waitcnt lgkmcnt(14)
	v_mfma_f32_32x32x16_bf16 v[50:65], v[162:165], v[118:121], v[50:65]
	v_add_f32_e32 v110, v88, v110
	v_add_f32_e32 v110, v89, v110
	v_add_f32_e32 v110, v90, v110
	v_add_f32_e32 v110, v91, v110
	v_cvt_pk_bf16_f32 v132, v86, v87
	v_cvt_pk_bf16_f32 v133, v88, v89
	ds_read_b64_tr_b16 v[86:87], v186 offset:27648
	ds_read_b64_tr_b16 v[88:89], v186 offset:28160
	s_waitcnt lgkmcnt(14)
	v_mfma_f32_32x32x16_bf16 v[66:81], v[158:161], v[114:117], v[66:81]
	v_add_f32_e32 v110, v92, v110
	v_add_f32_e32 v110, v93, v110
	v_add_f32_e32 v110, v94, v110
	v_add_f32_e32 v110, v95, v110
	v_cvt_pk_bf16_f32 v122, v90, v91
	v_cvt_pk_bf16_f32 v123, v92, v93
	ds_read_b64_tr_b16 v[90:91], v186 offset:31744
	ds_read_b64_tr_b16 v[92:93], v186 offset:32256
	v_mfma_f32_32x32x16_bf16 v[50:65], v[154:157], v[114:117], v[50:65]
	v_add_f32_e32 v110, v96, v110
	v_add_f32_e32 v110, v97, v110
	v_cvt_pk_bf16_f32 v124, v94, v95
	v_cvt_pk_bf16_f32 v125, v96, v97
	s_add_i32 s8, s18, s40
	s_mov_b32 m0, s8
	v_add_f32_e32 v208, v0, v110
	global_load_lds_dwordx4 v[184:185], off
	s_add_i32 s8, s44, s41
	s_mov_b32 m0, s8
	v_max_f32_e32 v94, v66, v67
	global_load_lds_dwordx4 v[182:183], off
	v_max3_f32 v95, v68, v69, v51
	v_max3_f32 v94, v94, v50, v52
	v_max3_f32 v94, v94, v53, v70
	v_max3_f32 v95, v95, v72, v73
	v_max3_f32 v94, v94, v71, v54
	v_max3_f32 v95, v95, v56, v57
	v_max3_f32 v94, v94, v55, v74
	v_max3_f32 v95, v95, v76, v77
	v_max3_f32 v94, v94, v75, v58
	v_max3_f32 v95, v95, v60, v61
	v_max3_f32 v94, v94, v59, v78
	v_max3_f32 v95, v95, v80, v81
	v_max3_f32 v94, v94, v79, v62
	v_max3_f32 v95, v95, v64, v65
	v_max3_f32 v0, v94, v63, v95
	v_mov_b32_e32 v94, v0
	s_nop 1
	v_permlane32_swap_b32_e32 v0, v94
	v_max_f32_e32 v0, v0, v94
	v_cmp_lt_f32_e32 vcc, s91, v0
	s_cmp_lg_u64 vcc, 0
	s_cselect_b64 s[8:9], -1, 0
	s_cbranch_vccnz .LBB0_209
